# GEMM K-loops (up, merge, GLU, W_in): back-edge rotation, loop-edge scalar work issued in the MFMA shadow of phase 3
# speedup vs baseline: 1.0038x; 1.0038x over previous
; #define PG8_STAGE(bufoff, gbase, voff) do { _Pragma("unroll") for (int _i = 0; _i < 2; ++_i) \
;         __builtin_amdgcn_global_load_lds((const unsigned*)((const char*)(gbase) + (voff)[_i]), (PG8_LAS unsigned*)(lds + (bufoff) + ldsw + _i * 8192), 16, 0, 0); } while (0)
; #define PG8_LDA(dst, b, h) do { _Pragma("unroll") for (int m = 0; m < 4; ++m) _Pragma("unroll") for (int k = 0; k < 2; ++k) dst[m][k] = *(const PG8_LAS bf16x8*)(lds + PG8_SA(b, h) + aoff + m * 2048 + k * 1024); } while (0)
; #define PG8_LDB(dst, b, h) do { _Pragma("unroll") for (int n = 0; n < 2; ++n) _Pragma("unroll") for (int k = 0; k < 2; ++k) dst[n][k] = *(const PG8_LAS bf16x8*)(lds + PG8_SB(b, h) + boff + n * 2048 + k * 1024); } while (0)
; #define PG8_MMA(ai, bj, At, Bt) do { __builtin_amdgcn_s_setprio(1); _Pragma("unroll") for (int m = 0; m < 4; ++m) _Pragma("unroll") for (int n = 0; n < 2; ++n) _Pragma("unroll") for (int k = 0; k < 2; ++k) \
;         acc[ai][bj][m][n] = __builtin_amdgcn_mfma_f32_16x16x32_bf16(Bt[n][k], At[m][k], acc[ai][bj][m][n], 0, 0, 0); __builtin_amdgcn_s_setprio(0); } while (0)
; #define PG8_WAIT_V(n) asm volatile("s_waitcnt vmcnt(" #n ")" ::: "memory")
; #define PG8_WAIT_L(n) asm volatile("s_waitcnt lgkmcnt(" #n ")" ::: "memory")
; #define PG8_BAR __builtin_amdgcn_s_barrier()
; #define PG8_SCHED __builtin_amdgcn_sched_barrier(0)
; template <class Epi, class Sched>
; __device__ __forceinline__ void gemm_phase(PG8_LAS unsigned char* lds, const Gemm g, const Sched& S, const Epi& E) {
;     ...
;         for (int t = 0; t < nt; t += 2) {
;             const bool last = (t == nt - 2);
;             const char* a1 = cA + (size_t)(t + 1) * kstep;
;             const char* a2 = last ? nA : cA + (size_t)(t + 2) * kstep; const char* b2 = last ? nB : cB + (size_t)(t + 2) * kstep;
;             const char* a3 = a2 + kstep; const char* b3 = b2 + kstep;
;             PG8_LDB(B0, 0, 0); PG8_LDB(B1, 0, 1); PG8_SCHED; PG8_LDA(At, 0, 0); PG8_STAGE(PG8_SA(1, 1), a1 + hstepA, voffA);
;             PG8_WAIT_V(8); PG8_WAIT_L(0); PG8_BAR; PG8_MMA(0, 0, At, B0); PG8_MMA(0, 1, At, B1); PG8_BAR; PG8_SCHED;
;             PG8_LDA(At, 0, 1); PG8_STAGE(PG8_SB(0, 0), b2, voffB); PG8_STAGE(PG8_SB(0, 1), b2 + hstepB, voffB); PG8_STAGE(PG8_SA(0, 0), a2, voffA);
;             PG8_WAIT_V(8); PG8_WAIT_L(0); PG8_BAR; PG8_MMA(1, 0, At, B0); PG8_MMA(1, 1, At, B1); PG8_BAR; PG8_SCHED;
.LBB0_24:
	s_add_u32 s9, s28, 0xfff80080
	s_addc_u32 s10, s29, -1
	s_add_i32 s11, 0, 0x10000
	s_cmp_eq_u32 s8, 28
	s_cselect_b32 s43, s5, s10
	s_cselect_b32 s42, s13, s9
	s_cselect_b32 s39, s59, s7
	s_cselect_b32 s38, s61, s6
	s_add_i32 s9, 0, 0x14000
.Lrot_24:
	v_add_u32_e32 v140, s11, v143
	ds_read_b128 v[146:149], v140
	ds_read_b128 v[150:153], v140 offset:1024
	ds_read_b128 v[154:157], v140 offset:2048
	ds_read_b128 v[158:161], v140 offset:3072
	v_add_u32_e32 v140, s9, v143
	ds_read_b128 v[170:173], v140
	ds_read_b128 v[174:177], v140 offset:1024
	ds_read_b128 v[178:181], v140 offset:2048
	ds_read_b128 v[182:185], v140 offset:3072
	v_lshl_add_u64 v[140:141], s[28:29], 0, v[136:137]
	s_add_i32 m0, s82, 0xc000
	ds_read_b128 v[186:189], v145
	ds_read_b128 v[190:193], v145 offset:1024
	ds_read_b128 v[194:197], v145 offset:2048
	ds_read_b128 v[198:201], v145 offset:3072
	ds_read_b128 v[202:205], v145 offset:4096
	ds_read_b128 v[216:219], v145 offset:5120
	ds_read_b128 v[220:223], v145 offset:6144
	ds_read_b128 v[224:227], v145 offset:7168
	global_load_lds_dwordx4 v[140:141], off
	v_lshl_add_u64 v[140:141], s[28:29], 0, v[138:139]
	s_add_i32 m0, s82, 0xe000
	s_nop 0
	global_load_lds_dwordx4 v[140:141], off
	s_waitcnt vmcnt(8)
	s_waitcnt lgkmcnt(0)
	s_barrier
	s_setprio 1
	s_waitcnt lgkmcnt(0)
	v_mfma_f32_16x16x32_bf16 v[118:121], v[146:149], v[186:189], v[118:121]
	v_mfma_f32_16x16x32_bf16 v[114:117], v[154:157], v[186:189], v[114:117]
	v_mfma_f32_16x16x32_bf16 v[110:113], v[146:149], v[194:197], v[110:113]
	v_mfma_f32_16x16x32_bf16 v[102:105], v[154:157], v[194:197], v[102:105]
	v_mfma_f32_16x16x32_bf16 v[86:89], v[146:149], v[202:205], v[86:89]
	v_mfma_f32_16x16x32_bf16 v[82:85], v[154:157], v[202:205], v[82:85]
	v_mfma_f32_16x16x32_bf16 v[78:81], v[146:149], v[220:223], v[78:81]
	v_mfma_f32_16x16x32_bf16 v[70:73], v[154:157], v[220:223], v[70:73]
	v_mfma_f32_16x16x32_bf16 v[118:121], v[150:153], v[190:193], v[118:121]
	v_mfma_f32_16x16x32_bf16 v[114:117], v[158:161], v[190:193], v[114:117]
	v_mfma_f32_16x16x32_bf16 v[110:113], v[150:153], v[198:201], v[110:113]
	v_mfma_f32_16x16x32_bf16 v[102:105], v[158:161], v[198:201], v[102:105]
	v_mfma_f32_16x16x32_bf16 v[86:89], v[150:153], v[216:219], v[86:89]
	v_mfma_f32_16x16x32_bf16 v[82:85], v[158:161], v[216:219], v[82:85]
	v_mfma_f32_16x16x32_bf16 v[78:81], v[150:153], v[224:227], v[78:81]
	v_mfma_f32_16x16x32_bf16 v[70:73], v[158:161], v[224:227], v[70:73]
	s_setprio 0
	s_setprio 1
	v_mfma_f32_16x16x32_bf16 v[126:129], v[170:173], v[186:189], v[126:129]
	v_mfma_f32_16x16x32_bf16 v[122:125], v[178:181], v[186:189], v[122:125]
	v_mfma_f32_16x16x32_bf16 v[106:109], v[170:173], v[194:197], v[106:109]
	v_mfma_f32_16x16x32_bf16 v[98:101], v[178:181], v[194:197], v[98:101]
	v_mfma_f32_16x16x32_bf16 v[94:97], v[170:173], v[202:205], v[94:97]
	v_mfma_f32_16x16x32_bf16 v[90:93], v[178:181], v[202:205], v[90:93]
	v_mfma_f32_16x16x32_bf16 v[74:77], v[170:173], v[220:223], v[74:77]
	v_mfma_f32_16x16x32_bf16 v[66:69], v[178:181], v[220:223], v[66:69]
	v_mfma_f32_16x16x32_bf16 v[126:129], v[174:177], v[190:193], v[126:129]
	v_mfma_f32_16x16x32_bf16 v[122:125], v[182:185], v[190:193], v[122:125]
	v_mfma_f32_16x16x32_bf16 v[106:109], v[174:177], v[198:201], v[106:109]
	v_mfma_f32_16x16x32_bf16 v[98:101], v[182:185], v[198:201], v[98:101]
	v_mfma_f32_16x16x32_bf16 v[94:97], v[174:177], v[216:219], v[94:97]
	v_mfma_f32_16x16x32_bf16 v[90:93], v[182:185], v[216:219], v[90:93]
	v_mfma_f32_16x16x32_bf16 v[74:77], v[174:177], v[224:227], v[74:77]
	v_mfma_f32_16x16x32_bf16 v[66:69], v[182:185], v[224:227], v[66:69]
	s_setprio 0
	s_barrier
	s_add_i32 s10, s11, s80
	v_lshl_add_u64 v[140:141], s[38:39], 0, v[0:1]
	s_mov_b32 m0, s10
	ds_read_b128 v[186:189], v145 offset:16384
	ds_read_b128 v[190:193], v145 offset:17408
	ds_read_b128 v[194:197], v145 offset:18432
	ds_read_b128 v[198:201], v145 offset:19456
	ds_read_b128 v[202:205], v145 offset:20480
	ds_read_b128 v[216:219], v145 offset:21504
	ds_read_b128 v[220:223], v145 offset:22528
	ds_read_b128 v[224:227], v145 offset:23552
	global_load_lds_dwordx4 v[140:141], off
	s_add_i32 m0, s10, 0x2000
	s_add_u32 s10, s38, 0x80000
	v_lshl_add_u64 v[168:169], s[38:39], 0, v[130:131]
	s_addc_u32 s11, s39, 0
	s_add_i32 s9, s9, s80
	global_load_lds_dwordx4 v[168:169], off
	v_lshl_add_u64 v[228:229], s[10:11], 0, v[0:1]
	s_mov_b32 m0, s9
	v_lshl_add_u64 v[230:231], s[42:43], 0, v[132:133]
	global_load_lds_dwordx4 v[228:229], off
	v_lshl_add_u64 v[228:229], s[10:11], 0, v[130:131]
	s_add_i32 m0, s9, 0x2000
	s_nop 0
	global_load_lds_dwordx4 v[228:229], off
	v_lshl_add_u64 v[228:229], s[42:43], 0, v[134:135]
	s_mov_b32 m0, s82
	s_nop 0
	global_load_lds_dwordx4 v[228:229], off
	s_mov_b32 m0, s83
	s_nop 0
	global_load_lds_dwordx4 v[230:231], off
	s_waitcnt vmcnt(8)
	s_waitcnt lgkmcnt(0)
	s_barrier
; #define PG8_STAGE(bufoff, gbase, voff) do { _Pragma("unroll") for (int _i = 0; _i < 2; ++_i) \
;         __builtin_amdgcn_global_load_lds((const unsigned*)((const char*)(gbase) + (voff)[_i]), (PG8_LAS unsigned*)(lds + (bufoff) + ldsw + _i * 8192), 16, 0, 0); } while (0)
; #define PG8_LDA(dst, b, h) do { _Pragma("unroll") for (int m = 0; m < 4; ++m) _Pragma("unroll") for (int k = 0; k < 2; ++k) dst[m][k] = *(const PG8_LAS bf16x8*)(lds + PG8_SA(b, h) + aoff + m * 2048 + k * 1024); } while (0)
; #define PG8_LDB(dst, b, h) do { _Pragma("unroll") for (int n = 0; n < 2; ++n) _Pragma("unroll") for (int k = 0; k < 2; ++k) dst[n][k] = *(const PG8_LAS bf16x8*)(lds + PG8_SB(b, h) + boff + n * 2048 + k * 1024); } while (0)
; #define PG8_MMA(ai, bj, At, Bt) do { __builtin_amdgcn_s_setprio(1); _Pragma("unroll") for (int m = 0; m < 4; ++m) _Pragma("unroll") for (int n = 0; n < 2; ++n) _Pragma("unroll") for (int k = 0; k < 2; ++k) \
;         acc[ai][bj][m][n] = __builtin_amdgcn_mfma_f32_16x16x32_bf16(Bt[n][k], At[m][k], acc[ai][bj][m][n], 0, 0, 0); __builtin_amdgcn_s_setprio(0); } while (0)
; #define PG8_WAIT_V(n) asm volatile("s_waitcnt vmcnt(" #n ")" ::: "memory")
; #define PG8_WAIT_L(n) asm volatile("s_waitcnt lgkmcnt(" #n ")" ::: "memory")
; #define PG8_BAR __builtin_amdgcn_s_barrier()
; #define PG8_SCHED __builtin_amdgcn_sched_barrier(0)
; template <class Epi, class Sched>
; __device__ __forceinline__ void gemm_phase(PG8_LAS unsigned char* lds, const Gemm g, const Sched& S, const Epi& E) {
;     ...
;             PG8_WAIT_V(8); PG8_WAIT_L(0); PG8_BAR; PG8_MMA(1, 0, At, B0); PG8_MMA(1, 1, At, B1); PG8_BAR; PG8_SCHED;
;             PG8_LDB(B0, 1, 0); PG8_LDB(B1, 1, 1); PG8_SCHED; PG8_LDA(At, 1, 0); PG8_STAGE(PG8_SA(0, 1), a2 + hstepA, voffA);
;             PG8_WAIT_V(8); PG8_WAIT_L(0); PG8_BAR; PG8_MMA(0, 0, At, B0); PG8_MMA(0, 1, At, B1); PG8_BAR; PG8_SCHED;
	s_setprio 1
	s_waitcnt lgkmcnt(0)
	v_mfma_f32_16x16x32_bf16 v[54:57], v[146:149], v[186:189], v[54:57]
	v_mfma_f32_16x16x32_bf16 v[50:53], v[154:157], v[186:189], v[50:53]
	v_mfma_f32_16x16x32_bf16 v[46:49], v[146:149], v[194:197], v[46:49]
	v_mfma_f32_16x16x32_bf16 v[38:41], v[154:157], v[194:197], v[38:41]
	v_mfma_f32_16x16x32_bf16 v[22:25], v[146:149], v[202:205], v[22:25]
	v_mfma_f32_16x16x32_bf16 v[18:21], v[154:157], v[202:205], v[18:21]
	v_mfma_f32_16x16x32_bf16 v[14:17], v[146:149], v[220:223], v[14:17]
	v_mfma_f32_16x16x32_bf16 v[6:9], v[154:157], v[220:223], v[6:9]
	v_mfma_f32_16x16x32_bf16 v[54:57], v[150:153], v[190:193], v[54:57]
	v_mfma_f32_16x16x32_bf16 v[50:53], v[158:161], v[190:193], v[50:53]
	v_mfma_f32_16x16x32_bf16 v[46:49], v[150:153], v[198:201], v[46:49]
	v_mfma_f32_16x16x32_bf16 v[38:41], v[158:161], v[198:201], v[38:41]
	v_mfma_f32_16x16x32_bf16 v[22:25], v[150:153], v[216:219], v[22:25]
	v_mfma_f32_16x16x32_bf16 v[18:21], v[158:161], v[216:219], v[18:21]
	v_mfma_f32_16x16x32_bf16 v[14:17], v[150:153], v[224:227], v[14:17]
	v_mfma_f32_16x16x32_bf16 v[6:9], v[158:161], v[224:227], v[6:9]
	s_setprio 0
	s_setprio 1
	v_mfma_f32_16x16x32_bf16 v[62:65], v[170:173], v[186:189], v[62:65]
	v_mfma_f32_16x16x32_bf16 v[58:61], v[178:181], v[186:189], v[58:61]
	v_mfma_f32_16x16x32_bf16 v[42:45], v[170:173], v[194:197], v[42:45]
	v_mfma_f32_16x16x32_bf16 v[34:37], v[178:181], v[194:197], v[34:37]
	v_mfma_f32_16x16x32_bf16 v[30:33], v[170:173], v[202:205], v[30:33]
	v_mfma_f32_16x16x32_bf16 v[26:29], v[178:181], v[202:205], v[26:29]
	v_mfma_f32_16x16x32_bf16 v[10:13], v[170:173], v[220:223], v[10:13]
	v_mfma_f32_16x16x32_bf16 v[2:5], v[178:181], v[220:223], v[2:5]
	v_mfma_f32_16x16x32_bf16 v[62:65], v[174:177], v[190:193], v[62:65]
	v_mfma_f32_16x16x32_bf16 v[58:61], v[182:185], v[190:193], v[58:61]
	v_mfma_f32_16x16x32_bf16 v[42:45], v[174:177], v[198:201], v[42:45]
	v_mfma_f32_16x16x32_bf16 v[34:37], v[182:185], v[198:201], v[34:37]
	v_mfma_f32_16x16x32_bf16 v[30:33], v[174:177], v[216:219], v[30:33]
	v_mfma_f32_16x16x32_bf16 v[26:29], v[182:185], v[216:219], v[26:29]
	v_mfma_f32_16x16x32_bf16 v[10:13], v[174:177], v[224:227], v[10:13]
	v_mfma_f32_16x16x32_bf16 v[2:5], v[182:185], v[224:227], v[2:5]
	s_setprio 0
	s_barrier
	s_add_i32 s9, 0, 0x18000
	s_add_i32 s57, 0, 0x1c000
	v_add_u32_e32 v158, s9, v143
	v_add_u32_e32 v162, s57, v143
	ds_read_b128 v[146:149], v158
	ds_read_b128 v[150:153], v158 offset:1024
	ds_read_b128 v[154:157], v158 offset:2048
	ds_read_b128 v[158:161], v158 offset:3072
	ds_read_b128 v[170:173], v162
	ds_read_b128 v[174:177], v162 offset:1024
	ds_read_b128 v[178:181], v162 offset:2048
	ds_read_b128 v[182:185], v162 offset:3072
	s_add_u32 s10, s42, 0x80000
	s_addc_u32 s11, s43, 0
	s_mov_b32 m0, s84
	v_lshl_add_u64 v[232:233], s[10:11], 0, v[134:135]
	ds_read_b128 v[186:189], v145 offset:32768
	ds_read_b128 v[190:193], v145 offset:33792
	ds_read_b128 v[194:197], v145 offset:34816
	ds_read_b128 v[198:201], v145 offset:35840
	ds_read_b128 v[202:205], v145 offset:36864
	ds_read_b128 v[216:219], v145 offset:37888
	ds_read_b128 v[220:223], v145 offset:38912
	ds_read_b128 v[224:227], v145 offset:39936
	global_load_lds_dwordx4 v[232:233], off
	v_lshl_add_u64 v[232:233], s[10:11], 0, v[132:133]
	s_mov_b32 m0, s85
	s_nop 0
	global_load_lds_dwordx4 v[232:233], off
	s_waitcnt vmcnt(8)
	s_waitcnt lgkmcnt(0)
	s_barrier
	s_setprio 1
	s_waitcnt lgkmcnt(0)
	v_mfma_f32_16x16x32_bf16 v[118:121], v[146:149], v[186:189], v[118:121]
	v_mfma_f32_16x16x32_bf16 v[114:117], v[154:157], v[186:189], v[114:117]
	v_mfma_f32_16x16x32_bf16 v[110:113], v[146:149], v[194:197], v[110:113]
	v_mfma_f32_16x16x32_bf16 v[102:105], v[154:157], v[194:197], v[102:105]
	v_mfma_f32_16x16x32_bf16 v[86:89], v[146:149], v[202:205], v[86:89]
	v_mfma_f32_16x16x32_bf16 v[82:85], v[154:157], v[202:205], v[82:85]
	v_mfma_f32_16x16x32_bf16 v[78:81], v[146:149], v[220:223], v[78:81]
	v_mfma_f32_16x16x32_bf16 v[70:73], v[154:157], v[220:223], v[70:73]
	v_mfma_f32_16x16x32_bf16 v[118:121], v[150:153], v[190:193], v[118:121]
	v_mfma_f32_16x16x32_bf16 v[114:117], v[158:161], v[190:193], v[114:117]
	v_mfma_f32_16x16x32_bf16 v[110:113], v[150:153], v[198:201], v[110:113]
	v_mfma_f32_16x16x32_bf16 v[102:105], v[158:161], v[198:201], v[102:105]
	v_mfma_f32_16x16x32_bf16 v[86:89], v[150:153], v[216:219], v[86:89]
	v_mfma_f32_16x16x32_bf16 v[82:85], v[158:161], v[216:219], v[82:85]
	v_mfma_f32_16x16x32_bf16 v[78:81], v[150:153], v[224:227], v[78:81]
	v_mfma_f32_16x16x32_bf16 v[70:73], v[158:161], v[224:227], v[70:73]
	s_setprio 0
	s_setprio 1
	v_mfma_f32_16x16x32_bf16 v[126:129], v[170:173], v[186:189], v[126:129]
	v_mfma_f32_16x16x32_bf16 v[122:125], v[178:181], v[186:189], v[122:125]
	v_mfma_f32_16x16x32_bf16 v[106:109], v[170:173], v[194:197], v[106:109]
	v_mfma_f32_16x16x32_bf16 v[98:101], v[178:181], v[194:197], v[98:101]
	v_mfma_f32_16x16x32_bf16 v[94:97], v[170:173], v[202:205], v[94:97]
	v_mfma_f32_16x16x32_bf16 v[90:93], v[178:181], v[202:205], v[90:93]
	v_mfma_f32_16x16x32_bf16 v[74:77], v[170:173], v[220:223], v[74:77]
	v_mfma_f32_16x16x32_bf16 v[66:69], v[178:181], v[220:223], v[66:69]
	v_mfma_f32_16x16x32_bf16 v[126:129], v[174:177], v[190:193], v[126:129]
	v_mfma_f32_16x16x32_bf16 v[122:125], v[182:185], v[190:193], v[122:125]
	v_mfma_f32_16x16x32_bf16 v[106:109], v[174:177], v[198:201], v[106:109]
	v_mfma_f32_16x16x32_bf16 v[98:101], v[182:185], v[198:201], v[98:101]
	v_mfma_f32_16x16x32_bf16 v[94:97], v[174:177], v[216:219], v[94:97]
	v_mfma_f32_16x16x32_bf16 v[90:93], v[182:185], v[216:219], v[90:93]
	v_mfma_f32_16x16x32_bf16 v[74:77], v[174:177], v[224:227], v[74:77]
	v_mfma_f32_16x16x32_bf16 v[66:69], v[182:185], v[224:227], v[66:69]
	s_setprio 0
	s_barrier
; #define PG8_STAGE(bufoff, gbase, voff) do { _Pragma("unroll") for (int _i = 0; _i < 2; ++_i) \
;         __builtin_amdgcn_global_load_lds((const unsigned*)((const char*)(gbase) + (voff)[_i]), (PG8_LAS unsigned*)(lds + (bufoff) + ldsw + _i * 8192), 16, 0, 0); } while (0)
; #define PG8_LDA(dst, b, h) do { _Pragma("unroll") for (int m = 0; m < 4; ++m) _Pragma("unroll") for (int k = 0; k < 2; ++k) dst[m][k] = *(const PG8_LAS bf16x8*)(lds + PG8_SA(b, h) + aoff + m * 2048 + k * 1024); } while (0)
; #define PG8_LDB(dst, b, h) do { _Pragma("unroll") for (int n = 0; n < 2; ++n) _Pragma("unroll") for (int k = 0; k < 2; ++k) dst[n][k] = *(const PG8_LAS bf16x8*)(lds + PG8_SB(b, h) + boff + n * 2048 + k * 1024); } while (0)
; #define PG8_WAIT_V(n) asm volatile("s_waitcnt vmcnt(" #n ")" ::: "memory")
; template <class Epi, class Sched>
; __device__ __forceinline__ void gemm_phase(PG8_LAS unsigned char* lds, const Gemm g, const Sched& S, const Epi& E) {
;     ...
;         for (int t = 0; t < nt; t += 2) {
;             const bool last = (t == nt - 2);
;             const char* a1 = cA + (size_t)(t + 1) * kstep;
;             const char* a2 = last ? nA : cA + (size_t)(t + 2) * kstep; const char* b2 = last ? nB : cB + (size_t)(t + 2) * kstep;
;             const char* a3 = a2 + kstep; const char* b3 = b2 + kstep;
;             PG8_LDB(B0, 0, 0); PG8_LDB(B1, 0, 1); PG8_SCHED; PG8_LDA(At, 0, 0); PG8_STAGE(PG8_SA(1, 1), a1 + hstepA, voffA);
;             PG8_WAIT_V(8); PG8_WAIT_L(0); PG8_BAR; PG8_MMA(0, 0, At, B0); PG8_MMA(0, 1, At, B1); PG8_BAR; PG8_SCHED;
;             PG8_LDA(At, 0, 1); PG8_STAGE(PG8_SB(0, 0), b2, voffB); PG8_STAGE(PG8_SB(0, 1), b2 + hstepB, voffB); PG8_STAGE(PG8_SA(0, 0), a2, voffA);
;             PG8_WAIT_V(8); PG8_WAIT_L(0); PG8_BAR; PG8_MMA(1, 0, At, B0); PG8_MMA(1, 1, At, B1); PG8_BAR; PG8_SCHED;
;             PG8_LDB(B0, 1, 0); PG8_LDB(B1, 1, 1); PG8_SCHED; PG8_LDA(At, 1, 0); PG8_STAGE(PG8_SA(0, 1), a2 + hstepA, voffA);
;             PG8_WAIT_V(8); PG8_WAIT_L(0); PG8_BAR; PG8_MMA(0, 0, At, B0); PG8_MMA(0, 1, At, B1); PG8_BAR; PG8_SCHED;
;             PG8_LDA(At, 1, 1); PG8_STAGE(PG8_SB(1, 0), b3, voffB); PG8_STAGE(PG8_SB(1, 1), b3 + hstepB, voffB); PG8_STAGE(PG8_SA(1, 0), a3, voffA);
;             PG8_WAIT_V(8); PG8_WAIT_L(0); PG8_BAR; PG8_MMA(1, 0, At, B0); PG8_MMA(1, 1, At, B1); PG8_BAR; PG8_SCHED;
;         }
;         if (wr == 0) PG8_BAR;
	s_add_i32 s9, s9, s80
	v_lshl_add_u64 v[140:141], v[140:141], 0, s[22:23]
	s_mov_b32 m0, s9
	ds_read_b128 v[186:189], v145 offset:49152
	ds_read_b128 v[190:193], v145 offset:50176
	ds_read_b128 v[194:197], v145 offset:51200
	ds_read_b128 v[198:201], v145 offset:52224
	ds_read_b128 v[202:205], v145 offset:53248
	ds_read_b128 v[216:219], v145 offset:54272
	ds_read_b128 v[220:223], v145 offset:55296
	ds_read_b128 v[224:227], v145 offset:56320
	global_load_lds_dwordx4 v[140:141], off
	s_add_i32 m0, s9, 0x2000
	s_add_u32 s10, s38, 0x80080
	v_lshl_add_u64 v[140:141], v[168:169], 0, s[22:23]
	s_addc_u32 s11, s39, 0
	s_add_i32 s9, s57, s80
	global_load_lds_dwordx4 v[140:141], off
	v_lshl_add_u64 v[140:141], s[10:11], 0, v[0:1]
	s_mov_b32 m0, s9
	s_nop 0
	global_load_lds_dwordx4 v[140:141], off
	v_lshl_add_u64 v[140:141], s[10:11], 0, v[130:131]
	s_add_i32 m0, s9, 0x2000
	s_nop 0
	global_load_lds_dwordx4 v[140:141], off
	v_lshl_add_u64 v[140:141], v[228:229], 0, s[22:23]
	s_mov_b32 m0, s20
	s_nop 0
	global_load_lds_dwordx4 v[140:141], off
	v_lshl_add_u64 v[140:141], v[230:231], 0, s[22:23]
	s_mov_b32 m0, s86
	s_nop 0
	global_load_lds_dwordx4 v[140:141], off
	s_waitcnt vmcnt(8)
	s_waitcnt lgkmcnt(0)
	s_barrier
	s_setprio 1
	s_waitcnt lgkmcnt(0)
	v_mfma_f32_16x16x32_bf16 v[54:57], v[146:149], v[186:189], v[54:57]
	v_mfma_f32_16x16x32_bf16 v[50:53], v[154:157], v[186:189], v[50:53]
	v_mfma_f32_16x16x32_bf16 v[46:49], v[146:149], v[194:197], v[46:49]
	v_mfma_f32_16x16x32_bf16 v[38:41], v[154:157], v[194:197], v[38:41]
	v_mfma_f32_16x16x32_bf16 v[22:25], v[146:149], v[202:205], v[22:25]
	v_mfma_f32_16x16x32_bf16 v[18:21], v[154:157], v[202:205], v[18:21]
	v_mfma_f32_16x16x32_bf16 v[14:17], v[146:149], v[220:223], v[14:17]
	v_mfma_f32_16x16x32_bf16 v[6:9], v[154:157], v[220:223], v[6:9]
	v_mfma_f32_16x16x32_bf16 v[54:57], v[150:153], v[190:193], v[54:57]
	v_mfma_f32_16x16x32_bf16 v[50:53], v[158:161], v[190:193], v[50:53]
	v_mfma_f32_16x16x32_bf16 v[46:49], v[150:153], v[198:201], v[46:49]
	v_mfma_f32_16x16x32_bf16 v[38:41], v[158:161], v[198:201], v[38:41]
	v_mfma_f32_16x16x32_bf16 v[22:25], v[150:153], v[216:219], v[22:25]
	v_mfma_f32_16x16x32_bf16 v[18:21], v[158:161], v[216:219], v[18:21]
	v_mfma_f32_16x16x32_bf16 v[14:17], v[150:153], v[224:227], v[14:17]
	v_mfma_f32_16x16x32_bf16 v[6:9], v[158:161], v[224:227], v[6:9]
	s_setprio 0
	s_setprio 1
	v_mfma_f32_16x16x32_bf16 v[62:65], v[170:173], v[186:189], v[62:65]
	v_mfma_f32_16x16x32_bf16 v[58:61], v[178:181], v[186:189], v[58:61]
	s_add_i32 s8, s8, 2
	v_mfma_f32_16x16x32_bf16 v[42:45], v[170:173], v[194:197], v[42:45]
	s_add_u32 s28, s28, 0x100
	v_mfma_f32_16x16x32_bf16 v[34:37], v[178:181], v[194:197], v[34:37]
	s_addc_u32 s29, s29, 0
	v_mfma_f32_16x16x32_bf16 v[30:33], v[170:173], v[202:205], v[30:33]
	s_add_u32 s6, s6, 0x100
	v_mfma_f32_16x16x32_bf16 v[26:29], v[178:181], v[202:205], v[26:29]
	s_addc_u32 s7, s7, 0
	v_mfma_f32_16x16x32_bf16 v[10:13], v[170:173], v[220:223], v[10:13]
	s_add_u32 s9, s28, 0xfff80080
	v_mfma_f32_16x16x32_bf16 v[2:5], v[178:181], v[220:223], v[2:5]
	s_addc_u32 s10, s29, -1
	v_mfma_f32_16x16x32_bf16 v[62:65], v[174:177], v[190:193], v[62:65]
	s_add_i32 s11, 0, 0x10000
	v_mfma_f32_16x16x32_bf16 v[58:61], v[182:185], v[190:193], v[58:61]
	s_cmp_eq_u32 s8, 28
	v_mfma_f32_16x16x32_bf16 v[42:45], v[174:177], v[198:201], v[42:45]
	s_cselect_b32 s43, s5, s10
	v_mfma_f32_16x16x32_bf16 v[34:37], v[182:185], v[198:201], v[34:37]
	s_cselect_b32 s42, s13, s9
	v_mfma_f32_16x16x32_bf16 v[30:33], v[174:177], v[216:219], v[30:33]
	s_cselect_b32 s39, s59, s7
	v_mfma_f32_16x16x32_bf16 v[26:29], v[182:185], v[216:219], v[26:29]
	s_cselect_b32 s38, s61, s6
	v_mfma_f32_16x16x32_bf16 v[10:13], v[174:177], v[224:227], v[10:13]
	s_add_i32 s9, 0, 0x14000
	v_mfma_f32_16x16x32_bf16 v[2:5], v[182:185], v[224:227], v[2:5]
	s_cmp_gt_u32 s8, 29
	s_setprio 0
	s_barrier
	s_cbranch_scc0 .Lrot_24
	s_and_b64 vcc, exec, s[50:51]
	s_cbranch_vccz .LBB0_27
	s_barrier

; #define PG8_STAGE(bufoff, gbase, voff) do { _Pragma("unroll") for (int _i = 0; _i < 2; ++_i) \
;         __builtin_amdgcn_global_load_lds((const unsigned*)((const char*)(gbase) + (voff)[_i]), (PG8_LAS unsigned*)(lds + (bufoff) + ldsw + _i * 8192), 16, 0, 0); } while (0)
; #define PG8_LDA(dst, b, h) do { _Pragma("unroll") for (int m = 0; m < 4; ++m) _Pragma("unroll") for (int k = 0; k < 2; ++k) dst[m][k] = *(const PG8_LAS bf16x8*)(lds + PG8_SA(b, h) + aoff + m * 2048 + k * 1024); } while (0)
; #define PG8_LDB(dst, b, h) do { _Pragma("unroll") for (int n = 0; n < 2; ++n) _Pragma("unroll") for (int k = 0; k < 2; ++k) dst[n][k] = *(const PG8_LAS bf16x8*)(lds + PG8_SB(b, h) + boff + n * 2048 + k * 1024); } while (0)
; #define PG8_MMA(ai, bj, At, Bt) do { __builtin_amdgcn_s_setprio(1); _Pragma("unroll") for (int m = 0; m < 4; ++m) _Pragma("unroll") for (int n = 0; n < 2; ++n) _Pragma("unroll") for (int k = 0; k < 2; ++k) \
;         acc[ai][bj][m][n] = __builtin_amdgcn_mfma_f32_16x16x32_bf16(Bt[n][k], At[m][k], acc[ai][bj][m][n], 0, 0, 0); __builtin_amdgcn_s_setprio(0); } while (0)
; #define PG8_WAIT_V(n) asm volatile("s_waitcnt vmcnt(" #n ")" ::: "memory")
; #define PG8_WAIT_L(n) asm volatile("s_waitcnt lgkmcnt(" #n ")" ::: "memory")
; #define PG8_BAR __builtin_amdgcn_s_barrier()
; #define PG8_SCHED __builtin_amdgcn_sched_barrier(0)
; template <class Epi, class Sched>
; __device__ __forceinline__ void gemm_phase(PG8_LAS unsigned char* lds, const Gemm g, const Sched& S, const Epi& E) {
;     ...
;         for (int t = 0; t < nt; t += 2) {
;             const bool last = (t == nt - 2);
;             const char* a1 = cA + (size_t)(t + 1) * kstep;
;             const char* a2 = last ? nA : cA + (size_t)(t + 2) * kstep; const char* b2 = last ? nB : cB + (size_t)(t + 2) * kstep;
;             const char* a3 = a2 + kstep; const char* b3 = b2 + kstep;
;             PG8_LDB(B0, 0, 0); PG8_LDB(B1, 0, 1); PG8_SCHED; PG8_LDA(At, 0, 0); PG8_STAGE(PG8_SA(1, 1), a1 + hstepA, voffA);
;             PG8_WAIT_V(8); PG8_WAIT_L(0); PG8_BAR; PG8_MMA(0, 0, At, B0); PG8_MMA(0, 1, At, B1); PG8_BAR; PG8_SCHED;
;             PG8_LDA(At, 0, 1); PG8_STAGE(PG8_SB(0, 0), b2, voffB); PG8_STAGE(PG8_SB(0, 1), b2 + hstepB, voffB); PG8_STAGE(PG8_SA(0, 0), a2, voffA);
;             PG8_WAIT_V(8); PG8_WAIT_L(0); PG8_BAR; PG8_MMA(1, 0, At, B0); PG8_MMA(1, 1, At, B1); PG8_BAR; PG8_SCHED;
.LBB0_132:
	s_add_u32 s10, s28, 0xfff80080
	s_addc_u32 s11, s29, -1
	s_add_i32 s76, 0, 0x10000
	s_cmp_eq_u32 s9, 12
	s_cselect_b32 vcc_hi, s67, s11
	s_cselect_b32 vcc_lo, s97, s10
	s_cselect_b32 s43, s65, s8
	s_cselect_b32 s42, s6, s7
	s_add_i32 s57, 0, 0x14000
.Lrot_132:
	v_add_u32_e32 v0, s76, v216
	ds_read_b128 v[66:69], v0
	ds_read_b128 v[78:81], v0 offset:1024
	ds_read_b128 v[90:93], v0 offset:2048
	ds_read_b128 v[102:105], v0 offset:3072
	v_add_u32_e32 v0, s57, v216
	ds_read_b128 v[146:149], v0
	ds_read_b128 v[150:153], v0 offset:1024
	ds_read_b128 v[154:157], v0 offset:2048
	ds_read_b128 v[158:161], v0 offset:3072
	v_lshl_add_u64 v[168:169], s[28:29], 0, v[178:179]
	s_add_i32 m0, s88, 0xc000
	ds_read_b128 v[182:185], v218
	ds_read_b128 v[186:189], v218 offset:1024
	ds_read_b128 v[190:193], v218 offset:2048
	ds_read_b128 v[194:197], v218 offset:3072
	ds_read_b128 v[198:201], v218 offset:4096
	ds_read_b128 v[202:205], v218 offset:5120
	ds_read_b128 v[220:223], v218 offset:6144
	ds_read_b128 v[224:227], v218 offset:7168
	global_load_lds_dwordx4 v[168:169], off
	v_lshl_add_u64 v[168:169], s[28:29], 0, v[180:181]
	s_add_i32 m0, s88, 0xe000
	s_nop 0
	global_load_lds_dwordx4 v[168:169], off
	s_waitcnt vmcnt(8)
	s_waitcnt lgkmcnt(0)
	s_barrier
	s_setprio 1
	s_waitcnt lgkmcnt(0)
	v_mfma_f32_16x16x32_bf16 v[142:145], v[66:69], v[182:185], v[142:145]
	v_mfma_f32_16x16x32_bf16 v[138:141], v[90:93], v[182:185], v[138:141]
	v_mfma_f32_16x16x32_bf16 v[134:137], v[66:69], v[190:193], v[134:137]
	v_mfma_f32_16x16x32_bf16 v[130:133], v[90:93], v[190:193], v[130:133]
	v_mfma_f32_16x16x32_bf16 v[126:129], v[66:69], v[198:201], v[126:129]
	v_mfma_f32_16x16x32_bf16 v[122:125], v[90:93], v[198:201], v[122:125]
	v_mfma_f32_16x16x32_bf16 v[118:121], v[66:69], v[220:223], v[118:121]
	v_mfma_f32_16x16x32_bf16 v[114:117], v[90:93], v[220:223], v[114:117]
	v_mfma_f32_16x16x32_bf16 v[142:145], v[78:81], v[186:189], v[142:145]
	v_mfma_f32_16x16x32_bf16 v[138:141], v[102:105], v[186:189], v[138:141]
	v_mfma_f32_16x16x32_bf16 v[134:137], v[78:81], v[194:197], v[134:137]
	v_mfma_f32_16x16x32_bf16 v[130:133], v[102:105], v[194:197], v[130:133]
	v_mfma_f32_16x16x32_bf16 v[126:129], v[78:81], v[202:205], v[126:129]
	v_mfma_f32_16x16x32_bf16 v[122:125], v[102:105], v[202:205], v[122:125]
	v_mfma_f32_16x16x32_bf16 v[118:121], v[78:81], v[224:227], v[118:121]
	v_mfma_f32_16x16x32_bf16 v[114:117], v[102:105], v[224:227], v[114:117]
	s_setprio 0
	s_setprio 1
	v_mfma_f32_16x16x32_bf16 v[62:65], v[146:149], v[182:185], v[62:65]
	v_mfma_f32_16x16x32_bf16 v[58:61], v[154:157], v[182:185], v[58:61]
	v_mfma_f32_16x16x32_bf16 v[54:57], v[146:149], v[190:193], v[54:57]
	v_mfma_f32_16x16x32_bf16 v[50:53], v[154:157], v[190:193], v[50:53]
	v_mfma_f32_16x16x32_bf16 v[46:49], v[146:149], v[198:201], v[46:49]
	v_mfma_f32_16x16x32_bf16 v[42:45], v[154:157], v[198:201], v[42:45]
	v_mfma_f32_16x16x32_bf16 v[38:41], v[146:149], v[220:223], v[38:41]
	v_mfma_f32_16x16x32_bf16 v[34:37], v[154:157], v[220:223], v[34:37]
	v_mfma_f32_16x16x32_bf16 v[62:65], v[150:153], v[186:189], v[62:65]
	v_mfma_f32_16x16x32_bf16 v[58:61], v[158:161], v[186:189], v[58:61]
	v_mfma_f32_16x16x32_bf16 v[54:57], v[150:153], v[194:197], v[54:57]
	v_mfma_f32_16x16x32_bf16 v[50:53], v[158:161], v[194:197], v[50:53]
	v_mfma_f32_16x16x32_bf16 v[46:49], v[150:153], v[202:205], v[46:49]
	v_mfma_f32_16x16x32_bf16 v[42:45], v[158:161], v[202:205], v[42:45]
	v_mfma_f32_16x16x32_bf16 v[38:41], v[150:153], v[224:227], v[38:41]
	v_mfma_f32_16x16x32_bf16 v[34:37], v[158:161], v[224:227], v[34:37]
	s_setprio 0
	s_barrier
	s_add_i32 s10, s76, s87
	v_lshl_add_u64 v[168:169], s[42:43], 0, v[174:175]
	s_mov_b32 m0, s10
	ds_read_b128 v[182:185], v218 offset:16384
	ds_read_b128 v[186:189], v218 offset:17408
	ds_read_b128 v[190:193], v218 offset:18432
	ds_read_b128 v[194:197], v218 offset:19456
	ds_read_b128 v[198:201], v218 offset:20480
	ds_read_b128 v[202:205], v218 offset:21504
	ds_read_b128 v[220:223], v218 offset:22528
	ds_read_b128 v[224:227], v218 offset:23552
	global_load_lds_dwordx4 v[168:169], off
	s_add_i32 m0, s10, 0x2000
	s_add_u32 s10, s42, 0x80000
	v_lshl_add_u64 v[228:229], s[42:43], 0, v[170:171]
	s_addc_u32 s11, s43, 0
	s_add_i32 s57, s57, s87
	global_load_lds_dwordx4 v[228:229], off
	v_lshl_add_u64 v[230:231], s[10:11], 0, v[174:175]
	s_mov_b32 m0, s57
	v_lshl_add_u64 v[232:233], vcc, 0, v[172:173]
	global_load_lds_dwordx4 v[230:231], off
	v_lshl_add_u64 v[230:231], s[10:11], 0, v[170:171]
	s_add_i32 m0, s57, 0x2000
	s_nop 0
	global_load_lds_dwordx4 v[230:231], off
	v_lshl_add_u64 v[230:231], vcc, 0, v[176:177]
	s_mov_b32 m0, s88
	s_nop 0
	global_load_lds_dwordx4 v[230:231], off
	s_mov_b32 m0, s89
	s_nop 0
	global_load_lds_dwordx4 v[232:233], off
	s_waitcnt vmcnt(8)
	s_waitcnt lgkmcnt(0)
	s_barrier
; #define PG8_STAGE(bufoff, gbase, voff) do { _Pragma("unroll") for (int _i = 0; _i < 2; ++_i) \
;         __builtin_amdgcn_global_load_lds((const unsigned*)((const char*)(gbase) + (voff)[_i]), (PG8_LAS unsigned*)(lds + (bufoff) + ldsw + _i * 8192), 16, 0, 0); } while (0)
; #define PG8_LDA(dst, b, h) do { _Pragma("unroll") for (int m = 0; m < 4; ++m) _Pragma("unroll") for (int k = 0; k < 2; ++k) dst[m][k] = *(const PG8_LAS bf16x8*)(lds + PG8_SA(b, h) + aoff + m * 2048 + k * 1024); } while (0)
; #define PG8_LDB(dst, b, h) do { _Pragma("unroll") for (int n = 0; n < 2; ++n) _Pragma("unroll") for (int k = 0; k < 2; ++k) dst[n][k] = *(const PG8_LAS bf16x8*)(lds + PG8_SB(b, h) + boff + n * 2048 + k * 1024); } while (0)
; #define PG8_MMA(ai, bj, At, Bt) do { __builtin_amdgcn_s_setprio(1); _Pragma("unroll") for (int m = 0; m < 4; ++m) _Pragma("unroll") for (int n = 0; n < 2; ++n) _Pragma("unroll") for (int k = 0; k < 2; ++k) \
;         acc[ai][bj][m][n] = __builtin_amdgcn_mfma_f32_16x16x32_bf16(Bt[n][k], At[m][k], acc[ai][bj][m][n], 0, 0, 0); __builtin_amdgcn_s_setprio(0); } while (0)
; #define PG8_WAIT_V(n) asm volatile("s_waitcnt vmcnt(" #n ")" ::: "memory")
; #define PG8_WAIT_L(n) asm volatile("s_waitcnt lgkmcnt(" #n ")" ::: "memory")
; #define PG8_BAR __builtin_amdgcn_s_barrier()
; #define PG8_SCHED __builtin_amdgcn_sched_barrier(0)
; template <class Epi, class Sched>
; __device__ __forceinline__ void gemm_phase(PG8_LAS unsigned char* lds, const Gemm g, const Sched& S, const Epi& E) {
;     ...
;             PG8_WAIT_V(8); PG8_WAIT_L(0); PG8_BAR; PG8_MMA(1, 0, At, B0); PG8_MMA(1, 1, At, B1); PG8_BAR; PG8_SCHED;
;             PG8_LDB(B0, 1, 0); PG8_LDB(B1, 1, 1); PG8_SCHED; PG8_LDA(At, 1, 0); PG8_STAGE(PG8_SA(0, 1), a2 + hstepA, voffA);
;             PG8_WAIT_V(8); PG8_WAIT_L(0); PG8_BAR; PG8_MMA(0, 0, At, B0); PG8_MMA(0, 1, At, B1); PG8_BAR; PG8_SCHED;
	s_setprio 1
	s_waitcnt lgkmcnt(0)
	v_mfma_f32_16x16x32_bf16 v[110:113], v[66:69], v[182:185], v[110:113]
	v_mfma_f32_16x16x32_bf16 v[106:109], v[90:93], v[182:185], v[106:109]
	v_mfma_f32_16x16x32_bf16 v[98:101], v[66:69], v[190:193], v[98:101]
	v_mfma_f32_16x16x32_bf16 v[94:97], v[90:93], v[190:193], v[94:97]
	v_mfma_f32_16x16x32_bf16 v[86:89], v[66:69], v[198:201], v[86:89]
	v_mfma_f32_16x16x32_bf16 v[82:85], v[90:93], v[198:201], v[82:85]
	v_mfma_f32_16x16x32_bf16 v[70:73], v[90:93], v[220:223], v[70:73]
	v_mfma_f32_16x16x32_bf16 v[110:113], v[78:81], v[186:189], v[110:113]
	v_mfma_f32_16x16x32_bf16 v[106:109], v[102:105], v[186:189], v[106:109]
	v_mfma_f32_16x16x32_bf16 v[98:101], v[78:81], v[194:197], v[98:101]
	v_mfma_f32_16x16x32_bf16 v[94:97], v[102:105], v[194:197], v[94:97]
	v_mfma_f32_16x16x32_bf16 v[86:89], v[78:81], v[202:205], v[86:89]
	v_mfma_f32_16x16x32_bf16 v[82:85], v[102:105], v[202:205], v[82:85]
	v_mfma_f32_16x16x32_bf16 v[66:69], v[66:69], v[220:223], v[74:77]
	v_mfma_f32_16x16x32_bf16 v[70:73], v[102:105], v[224:227], v[70:73]
	v_mfma_f32_16x16x32_bf16 v[66:69], v[78:81], v[224:227], v[66:69]
	s_setprio 0
	s_setprio 1
	v_mfma_f32_16x16x32_bf16 v[30:33], v[146:149], v[182:185], v[30:33]
	v_mfma_f32_16x16x32_bf16 v[26:29], v[154:157], v[182:185], v[26:29]
	v_mfma_f32_16x16x32_bf16 v[22:25], v[146:149], v[190:193], v[22:25]
	v_mfma_f32_16x16x32_bf16 v[18:21], v[154:157], v[190:193], v[18:21]
	v_mfma_f32_16x16x32_bf16 v[14:17], v[146:149], v[198:201], v[14:17]
	v_mfma_f32_16x16x32_bf16 v[10:13], v[154:157], v[198:201], v[10:13]
	v_mfma_f32_16x16x32_bf16 v[6:9], v[146:149], v[220:223], v[6:9]
	v_mfma_f32_16x16x32_bf16 v[2:5], v[154:157], v[220:223], v[2:5]
	v_mfma_f32_16x16x32_bf16 v[30:33], v[150:153], v[186:189], v[30:33]
	v_mfma_f32_16x16x32_bf16 v[26:29], v[158:161], v[186:189], v[26:29]
	v_mfma_f32_16x16x32_bf16 v[22:25], v[150:153], v[194:197], v[22:25]
	v_mfma_f32_16x16x32_bf16 v[18:21], v[158:161], v[194:197], v[18:21]
	v_mfma_f32_16x16x32_bf16 v[14:17], v[150:153], v[202:205], v[14:17]
	v_mfma_f32_16x16x32_bf16 v[10:13], v[158:161], v[202:205], v[10:13]
	v_mfma_f32_16x16x32_bf16 v[6:9], v[150:153], v[224:227], v[6:9]
	v_mfma_f32_16x16x32_bf16 v[2:5], v[158:161], v[224:227], v[2:5]
	s_setprio 0
	s_barrier
	s_add_i32 s57, 0, 0x18000
	v_add_u32_e32 v0, s57, v216
	s_add_i32 s76, 0, 0x1c000
	ds_read_b128 v[74:77], v0
	ds_read_b128 v[78:81], v0 offset:1024
	ds_read_b128 v[90:93], v0 offset:2048
	ds_read_b128 v[102:105], v0 offset:3072
	v_add_u32_e32 v0, s76, v216
	ds_read_b128 v[146:149], v0
	ds_read_b128 v[150:153], v0 offset:1024
	ds_read_b128 v[154:157], v0 offset:2048
	ds_read_b128 v[158:161], v0 offset:3072
	s_add_u32 s10, vcc_lo, 0x80000
	s_addc_u32 s11, vcc_hi, 0
	s_mov_b32 m0, s90
	v_lshl_add_u64 v[234:235], s[10:11], 0, v[176:177]
	ds_read_b128 v[182:185], v218 offset:32768
	ds_read_b128 v[186:189], v218 offset:33792
	ds_read_b128 v[190:193], v218 offset:34816
	ds_read_b128 v[194:197], v218 offset:35840
	ds_read_b128 v[198:201], v218 offset:36864
	ds_read_b128 v[202:205], v218 offset:37888
	ds_read_b128 v[220:223], v218 offset:38912
	ds_read_b128 v[224:227], v218 offset:39936
	global_load_lds_dwordx4 v[234:235], off
	v_lshl_add_u64 v[234:235], s[10:11], 0, v[172:173]
	s_mov_b32 m0, s91
	s_nop 0
	global_load_lds_dwordx4 v[234:235], off
	s_waitcnt vmcnt(8)
	s_waitcnt lgkmcnt(0)
	s_barrier
	s_setprio 1
	s_waitcnt lgkmcnt(0)
	v_mfma_f32_16x16x32_bf16 v[142:145], v[74:77], v[182:185], v[142:145]
	v_mfma_f32_16x16x32_bf16 v[138:141], v[90:93], v[182:185], v[138:141]
	v_mfma_f32_16x16x32_bf16 v[134:137], v[74:77], v[190:193], v[134:137]
	v_mfma_f32_16x16x32_bf16 v[130:133], v[90:93], v[190:193], v[130:133]
	v_mfma_f32_16x16x32_bf16 v[126:129], v[74:77], v[198:201], v[126:129]
	v_mfma_f32_16x16x32_bf16 v[122:125], v[90:93], v[198:201], v[122:125]
	v_mfma_f32_16x16x32_bf16 v[118:121], v[74:77], v[220:223], v[118:121]
	v_mfma_f32_16x16x32_bf16 v[114:117], v[90:93], v[220:223], v[114:117]
	v_mfma_f32_16x16x32_bf16 v[142:145], v[78:81], v[186:189], v[142:145]
	v_mfma_f32_16x16x32_bf16 v[138:141], v[102:105], v[186:189], v[138:141]
	v_mfma_f32_16x16x32_bf16 v[134:137], v[78:81], v[194:197], v[134:137]
	v_mfma_f32_16x16x32_bf16 v[130:133], v[102:105], v[194:197], v[130:133]
	v_mfma_f32_16x16x32_bf16 v[126:129], v[78:81], v[202:205], v[126:129]
	v_mfma_f32_16x16x32_bf16 v[122:125], v[102:105], v[202:205], v[122:125]
	v_mfma_f32_16x16x32_bf16 v[118:121], v[78:81], v[224:227], v[118:121]
	v_mfma_f32_16x16x32_bf16 v[114:117], v[102:105], v[224:227], v[114:117]
	s_setprio 0
	s_setprio 1
	v_mfma_f32_16x16x32_bf16 v[62:65], v[146:149], v[182:185], v[62:65]
	v_mfma_f32_16x16x32_bf16 v[58:61], v[154:157], v[182:185], v[58:61]
	v_mfma_f32_16x16x32_bf16 v[54:57], v[146:149], v[190:193], v[54:57]
	v_mfma_f32_16x16x32_bf16 v[50:53], v[154:157], v[190:193], v[50:53]
	v_mfma_f32_16x16x32_bf16 v[46:49], v[146:149], v[198:201], v[46:49]
	v_mfma_f32_16x16x32_bf16 v[42:45], v[154:157], v[198:201], v[42:45]
	v_mfma_f32_16x16x32_bf16 v[38:41], v[146:149], v[220:223], v[38:41]
	v_mfma_f32_16x16x32_bf16 v[34:37], v[154:157], v[220:223], v[34:37]
	v_mfma_f32_16x16x32_bf16 v[62:65], v[150:153], v[186:189], v[62:65]
	v_mfma_f32_16x16x32_bf16 v[58:61], v[158:161], v[186:189], v[58:61]
	v_mfma_f32_16x16x32_bf16 v[54:57], v[150:153], v[194:197], v[54:57]
	v_mfma_f32_16x16x32_bf16 v[50:53], v[158:161], v[194:197], v[50:53]
	v_mfma_f32_16x16x32_bf16 v[46:49], v[150:153], v[202:205], v[46:49]
	v_mfma_f32_16x16x32_bf16 v[42:45], v[158:161], v[202:205], v[42:45]
	v_mfma_f32_16x16x32_bf16 v[38:41], v[150:153], v[224:227], v[38:41]
	v_mfma_f32_16x16x32_bf16 v[34:37], v[158:161], v[224:227], v[34:37]
	s_setprio 0
	s_barrier
; #define PG8_STAGE(bufoff, gbase, voff) do { _Pragma("unroll") for (int _i = 0; _i < 2; ++_i) \
;         __builtin_amdgcn_global_load_lds((const unsigned*)((const char*)(gbase) + (voff)[_i]), (PG8_LAS unsigned*)(lds + (bufoff) + ldsw + _i * 8192), 16, 0, 0); } while (0)
; #define PG8_LDA(dst, b, h) do { _Pragma("unroll") for (int m = 0; m < 4; ++m) _Pragma("unroll") for (int k = 0; k < 2; ++k) dst[m][k] = *(const PG8_LAS bf16x8*)(lds + PG8_SA(b, h) + aoff + m * 2048 + k * 1024); } while (0)
; #define PG8_LDB(dst, b, h) do { _Pragma("unroll") for (int n = 0; n < 2; ++n) _Pragma("unroll") for (int k = 0; k < 2; ++k) dst[n][k] = *(const PG8_LAS bf16x8*)(lds + PG8_SB(b, h) + boff + n * 2048 + k * 1024); } while (0)
; #define PG8_WAIT_V(n) asm volatile("s_waitcnt vmcnt(" #n ")" ::: "memory")
; template <class Epi, class Sched>
; __device__ __forceinline__ void gemm_phase(PG8_LAS unsigned char* lds, const Gemm g, const Sched& S, const Epi& E) {
;     ...
;         for (int t = 0; t < nt; t += 2) {
;             const bool last = (t == nt - 2);
;             const char* a1 = cA + (size_t)(t + 1) * kstep;
;             const char* a2 = last ? nA : cA + (size_t)(t + 2) * kstep; const char* b2 = last ? nB : cB + (size_t)(t + 2) * kstep;
;             const char* a3 = a2 + kstep; const char* b3 = b2 + kstep;
;             PG8_LDB(B0, 0, 0); PG8_LDB(B1, 0, 1); PG8_SCHED; PG8_LDA(At, 0, 0); PG8_STAGE(PG8_SA(1, 1), a1 + hstepA, voffA);
;             PG8_WAIT_V(8); PG8_WAIT_L(0); PG8_BAR; PG8_MMA(0, 0, At, B0); PG8_MMA(0, 1, At, B1); PG8_BAR; PG8_SCHED;
;             PG8_LDA(At, 0, 1); PG8_STAGE(PG8_SB(0, 0), b2, voffB); PG8_STAGE(PG8_SB(0, 1), b2 + hstepB, voffB); PG8_STAGE(PG8_SA(0, 0), a2, voffA);
;             PG8_WAIT_V(8); PG8_WAIT_L(0); PG8_BAR; PG8_MMA(1, 0, At, B0); PG8_MMA(1, 1, At, B1); PG8_BAR; PG8_SCHED;
;             PG8_LDB(B0, 1, 0); PG8_LDB(B1, 1, 1); PG8_SCHED; PG8_LDA(At, 1, 0); PG8_STAGE(PG8_SA(0, 1), a2 + hstepA, voffA);
;             PG8_WAIT_V(8); PG8_WAIT_L(0); PG8_BAR; PG8_MMA(0, 0, At, B0); PG8_MMA(0, 1, At, B1); PG8_BAR; PG8_SCHED;
;             PG8_LDA(At, 1, 1); PG8_STAGE(PG8_SB(1, 0), b3, voffB); PG8_STAGE(PG8_SB(1, 1), b3 + hstepB, voffB); PG8_STAGE(PG8_SA(1, 0), a3, voffA);
;             PG8_WAIT_V(8); PG8_WAIT_L(0); PG8_BAR; PG8_MMA(1, 0, At, B0); PG8_MMA(1, 1, At, B1); PG8_BAR; PG8_SCHED;
;         }
;         if (wr == 0) PG8_BAR;
	s_add_i32 s10, s57, s87
	v_lshl_add_u64 v[168:169], v[168:169], 0, s[22:23]
	s_mov_b32 m0, s10
	ds_read_b128 v[182:185], v218 offset:49152
	ds_read_b128 v[186:189], v218 offset:50176
	ds_read_b128 v[190:193], v218 offset:51200
	ds_read_b128 v[194:197], v218 offset:52224
	ds_read_b128 v[198:201], v218 offset:53248
	ds_read_b128 v[202:205], v218 offset:54272
	ds_read_b128 v[220:223], v218 offset:55296
	ds_read_b128 v[224:227], v218 offset:56320
	global_load_lds_dwordx4 v[168:169], off
	s_add_i32 m0, s10, 0x2000
	s_add_u32 s10, s42, 0x80080
	v_lshl_add_u64 v[168:169], v[228:229], 0, s[22:23]
	s_addc_u32 s11, s43, 0
	s_add_i32 s42, s76, s87
	global_load_lds_dwordx4 v[168:169], off
	v_lshl_add_u64 v[168:169], s[10:11], 0, v[174:175]
	s_mov_b32 m0, s42
	s_nop 0
	global_load_lds_dwordx4 v[168:169], off
	v_lshl_add_u64 v[168:169], s[10:11], 0, v[170:171]
	s_add_i32 m0, s42, 0x2000
	s_nop 0
	global_load_lds_dwordx4 v[168:169], off
	v_lshl_add_u64 v[168:169], v[230:231], 0, s[22:23]
	s_mov_b32 m0, s94
	s_nop 0
	global_load_lds_dwordx4 v[168:169], off
	v_lshl_add_u64 v[168:169], v[232:233], 0, s[22:23]
	s_mov_b32 m0, s95
	s_nop 0
	global_load_lds_dwordx4 v[168:169], off
	s_waitcnt vmcnt(8)
	s_waitcnt lgkmcnt(0)
	s_barrier
	s_setprio 1
	s_waitcnt lgkmcnt(0)
	v_mfma_f32_16x16x32_bf16 v[66:69], v[74:77], v[220:223], v[66:69]
	v_mfma_f32_16x16x32_bf16 v[110:113], v[74:77], v[182:185], v[110:113]
	v_mfma_f32_16x16x32_bf16 v[106:109], v[90:93], v[182:185], v[106:109]
	v_mfma_f32_16x16x32_bf16 v[98:101], v[74:77], v[190:193], v[98:101]
	v_mfma_f32_16x16x32_bf16 v[94:97], v[90:93], v[190:193], v[94:97]
	v_mfma_f32_16x16x32_bf16 v[86:89], v[74:77], v[198:201], v[86:89]
	v_mfma_f32_16x16x32_bf16 v[82:85], v[90:93], v[198:201], v[82:85]
	v_mfma_f32_16x16x32_bf16 v[74:77], v[78:81], v[224:227], v[66:69]
	v_mfma_f32_16x16x32_bf16 v[66:69], v[90:93], v[220:223], v[70:73]
	v_mfma_f32_16x16x32_bf16 v[110:113], v[78:81], v[186:189], v[110:113]
	v_mfma_f32_16x16x32_bf16 v[106:109], v[102:105], v[186:189], v[106:109]
	v_mfma_f32_16x16x32_bf16 v[98:101], v[78:81], v[194:197], v[98:101]
	v_mfma_f32_16x16x32_bf16 v[94:97], v[102:105], v[194:197], v[94:97]
	v_mfma_f32_16x16x32_bf16 v[86:89], v[78:81], v[202:205], v[86:89]
	v_mfma_f32_16x16x32_bf16 v[82:85], v[102:105], v[202:205], v[82:85]
	v_mfma_f32_16x16x32_bf16 v[70:73], v[102:105], v[224:227], v[66:69]
	s_setprio 0
	s_setprio 1
	v_mfma_f32_16x16x32_bf16 v[30:33], v[146:149], v[182:185], v[30:33]
	v_mfma_f32_16x16x32_bf16 v[26:29], v[154:157], v[182:185], v[26:29]
	s_add_i32 s9, s9, 2
	v_mfma_f32_16x16x32_bf16 v[22:25], v[146:149], v[190:193], v[22:25]
	s_add_u32 s28, s28, 0x100
	v_mfma_f32_16x16x32_bf16 v[18:21], v[154:157], v[190:193], v[18:21]
	s_addc_u32 s29, s29, 0
	v_mfma_f32_16x16x32_bf16 v[14:17], v[146:149], v[198:201], v[14:17]
	s_add_u32 s7, s7, 0x100
	v_mfma_f32_16x16x32_bf16 v[10:13], v[154:157], v[198:201], v[10:13]
	s_addc_u32 s8, s8, 0
	v_mfma_f32_16x16x32_bf16 v[6:9], v[146:149], v[220:223], v[6:9]
	s_add_u32 s10, s28, 0xfff80080
	v_mfma_f32_16x16x32_bf16 v[2:5], v[154:157], v[220:223], v[2:5]
	s_addc_u32 s11, s29, -1
	v_mfma_f32_16x16x32_bf16 v[30:33], v[150:153], v[186:189], v[30:33]
	s_add_i32 s76, 0, 0x10000
	v_mfma_f32_16x16x32_bf16 v[26:29], v[158:161], v[186:189], v[26:29]
	s_cmp_eq_u32 s9, 12
	v_mfma_f32_16x16x32_bf16 v[22:25], v[150:153], v[194:197], v[22:25]
	s_cselect_b32 vcc_hi, s67, s11
	v_mfma_f32_16x16x32_bf16 v[18:21], v[158:161], v[194:197], v[18:21]
	s_cselect_b32 vcc_lo, s97, s10
	v_mfma_f32_16x16x32_bf16 v[14:17], v[150:153], v[202:205], v[14:17]
	s_cselect_b32 s43, s65, s8
	v_mfma_f32_16x16x32_bf16 v[10:13], v[158:161], v[202:205], v[10:13]
	s_cselect_b32 s42, s6, s7
	v_mfma_f32_16x16x32_bf16 v[6:9], v[150:153], v[224:227], v[6:9]
	s_add_i32 s57, 0, 0x14000
	v_mfma_f32_16x16x32_bf16 v[2:5], v[158:161], v[224:227], v[2:5]
	s_cmp_gt_u32 s9, 13
	s_setprio 0
	s_barrier
	s_cbranch_scc0 .Lrot_132
	s_and_b64 vcc, exec, s[60:61]
	s_cbranch_vccz .LBB0_135
	s_barrier

; #define PG8_STAGE(bufoff, gbase, voff) do { _Pragma("unroll") for (int _i = 0; _i < 2; ++_i) \
;         __builtin_amdgcn_global_load_lds((const unsigned*)((const char*)(gbase) + (voff)[_i]), (PG8_LAS unsigned*)(lds + (bufoff) + ldsw + _i * 8192), 16, 0, 0); } while (0)
; #define PG8_LDA(dst, b, h) do { _Pragma("unroll") for (int m = 0; m < 4; ++m) _Pragma("unroll") for (int k = 0; k < 2; ++k) dst[m][k] = *(const PG8_LAS bf16x8*)(lds + PG8_SA(b, h) + aoff + m * 2048 + k * 1024); } while (0)
; #define PG8_LDB(dst, b, h) do { _Pragma("unroll") for (int n = 0; n < 2; ++n) _Pragma("unroll") for (int k = 0; k < 2; ++k) dst[n][k] = *(const PG8_LAS bf16x8*)(lds + PG8_SB(b, h) + boff + n * 2048 + k * 1024); } while (0)
; #define PG8_MMA(ai, bj, At, Bt) do { __builtin_amdgcn_s_setprio(1); _Pragma("unroll") for (int m = 0; m < 4; ++m) _Pragma("unroll") for (int n = 0; n < 2; ++n) _Pragma("unroll") for (int k = 0; k < 2; ++k) \
;         acc[ai][bj][m][n] = __builtin_amdgcn_mfma_f32_16x16x32_bf16(Bt[n][k], At[m][k], acc[ai][bj][m][n], 0, 0, 0); __builtin_amdgcn_s_setprio(0); } while (0)
; #define PG8_WAIT_V(n) asm volatile("s_waitcnt vmcnt(" #n ")" ::: "memory")
; #define PG8_WAIT_L(n) asm volatile("s_waitcnt lgkmcnt(" #n ")" ::: "memory")
; #define PG8_BAR __builtin_amdgcn_s_barrier()
; #define PG8_SCHED __builtin_amdgcn_sched_barrier(0)
; template <class Epi, class Sched>
; __device__ __forceinline__ void gemm_phase(PG8_LAS unsigned char* lds, const Gemm g, const Sched& S, const Epi& E) {
;     ...
;         for (int t = 0; t < nt; t += 2) {
;             const bool last = (t == nt - 2);
;             const char* a1 = cA + (size_t)(t + 1) * kstep;
;             const char* a2 = last ? nA : cA + (size_t)(t + 2) * kstep; const char* b2 = last ? nB : cB + (size_t)(t + 2) * kstep;
;             const char* a3 = a2 + kstep; const char* b3 = b2 + kstep;
;             PG8_LDB(B0, 0, 0); PG8_LDB(B1, 0, 1); PG8_SCHED; PG8_LDA(At, 0, 0); PG8_STAGE(PG8_SA(1, 1), a1 + hstepA, voffA);
;             PG8_WAIT_V(8); PG8_WAIT_L(0); PG8_BAR; PG8_MMA(0, 0, At, B0); PG8_MMA(0, 1, At, B1); PG8_BAR; PG8_SCHED;
;             PG8_LDA(At, 0, 1); PG8_STAGE(PG8_SB(0, 0), b2, voffB); PG8_STAGE(PG8_SB(0, 1), b2 + hstepB, voffB); PG8_STAGE(PG8_SA(0, 0), a2, voffA);
;             PG8_WAIT_V(8); PG8_WAIT_L(0); PG8_BAR; PG8_MMA(1, 0, At, B0); PG8_MMA(1, 1, At, B1); PG8_BAR; PG8_SCHED;
.Lrot_197:
	v_add_u32_e32 v142, s11, v216
	v_add_u32_e32 v168, s9, v216
	ds_read_b128 v[130:133], v142
	ds_read_b128 v[134:137], v142 offset:1024
	ds_read_b128 v[138:141], v142 offset:2048
	ds_read_b128 v[142:145], v142 offset:3072
	ds_read_b128 v[146:149], v168
	ds_read_b128 v[150:153], v168 offset:1024
	ds_read_b128 v[154:157], v168 offset:2048
	ds_read_b128 v[176:179], v168 offset:3072
	v_lshl_add_u64 v[168:169], s[28:29], 0, v[172:173]
	s_add_i32 m0, s61, 0xc000
	ds_read_b128 v[180:183], v218
	ds_read_b128 v[184:187], v218 offset:1024
	ds_read_b128 v[188:191], v218 offset:2048
	ds_read_b128 v[192:195], v218 offset:3072
	ds_read_b128 v[196:199], v218 offset:4096
	ds_read_b128 v[200:203], v218 offset:5120
	ds_read_b128 v[220:223], v218 offset:6144
	ds_read_b128 v[224:227], v218 offset:7168
	global_load_lds_dwordx4 v[168:169], off
	v_lshl_add_u64 v[168:169], s[28:29], 0, v[174:175]
	s_add_i32 m0, s61, 0xe000
	s_nop 0
	global_load_lds_dwordx4 v[168:169], off
	s_waitcnt vmcnt(8)
	s_waitcnt lgkmcnt(0)
	s_barrier
	s_setprio 1
	s_waitcnt lgkmcnt(0)
	v_mfma_f32_16x16x32_bf16 v[126:129], v[130:133], v[180:183], v[126:129]
	v_mfma_f32_16x16x32_bf16 v[122:125], v[138:141], v[180:183], v[122:125]
	v_mfma_f32_16x16x32_bf16 v[118:121], v[130:133], v[188:191], v[118:121]
	v_mfma_f32_16x16x32_bf16 v[114:117], v[138:141], v[188:191], v[114:117]
	v_mfma_f32_16x16x32_bf16 v[110:113], v[130:133], v[196:199], v[110:113]
	v_mfma_f32_16x16x32_bf16 v[106:109], v[138:141], v[196:199], v[106:109]
	v_mfma_f32_16x16x32_bf16 v[102:105], v[130:133], v[220:223], v[102:105]
	v_mfma_f32_16x16x32_bf16 v[98:101], v[138:141], v[220:223], v[98:101]
	v_mfma_f32_16x16x32_bf16 v[126:129], v[134:137], v[184:187], v[126:129]
	v_mfma_f32_16x16x32_bf16 v[122:125], v[142:145], v[184:187], v[122:125]
	v_mfma_f32_16x16x32_bf16 v[118:121], v[134:137], v[192:195], v[118:121]
	v_mfma_f32_16x16x32_bf16 v[114:117], v[142:145], v[192:195], v[114:117]
	v_mfma_f32_16x16x32_bf16 v[110:113], v[134:137], v[200:203], v[110:113]
	v_mfma_f32_16x16x32_bf16 v[106:109], v[142:145], v[200:203], v[106:109]
	v_mfma_f32_16x16x32_bf16 v[102:105], v[134:137], v[224:227], v[102:105]
	v_mfma_f32_16x16x32_bf16 v[98:101], v[142:145], v[224:227], v[98:101]
	s_setprio 0
	s_setprio 1
	v_mfma_f32_16x16x32_bf16 v[62:65], v[146:149], v[180:183], v[62:65]
	v_mfma_f32_16x16x32_bf16 v[58:61], v[154:157], v[180:183], v[58:61]
	v_mfma_f32_16x16x32_bf16 v[54:57], v[146:149], v[188:191], v[54:57]
	v_mfma_f32_16x16x32_bf16 v[50:53], v[154:157], v[188:191], v[50:53]
	v_mfma_f32_16x16x32_bf16 v[46:49], v[146:149], v[196:199], v[46:49]
	v_mfma_f32_16x16x32_bf16 v[42:45], v[154:157], v[196:199], v[42:45]
	v_mfma_f32_16x16x32_bf16 v[38:41], v[146:149], v[220:223], v[38:41]
	v_mfma_f32_16x16x32_bf16 v[34:37], v[154:157], v[220:223], v[34:37]
	v_mfma_f32_16x16x32_bf16 v[62:65], v[150:153], v[184:187], v[62:65]
	v_mfma_f32_16x16x32_bf16 v[58:61], v[176:179], v[184:187], v[58:61]
	v_mfma_f32_16x16x32_bf16 v[54:57], v[150:153], v[192:195], v[54:57]
	v_mfma_f32_16x16x32_bf16 v[50:53], v[176:179], v[192:195], v[50:53]
	v_mfma_f32_16x16x32_bf16 v[46:49], v[150:153], v[200:203], v[46:49]
	v_mfma_f32_16x16x32_bf16 v[42:45], v[176:179], v[200:203], v[42:45]
	v_mfma_f32_16x16x32_bf16 v[38:41], v[150:153], v[224:227], v[38:41]
	v_mfma_f32_16x16x32_bf16 v[34:37], v[176:179], v[224:227], v[34:37]
	s_setprio 0
	s_barrier
	s_add_i32 s10, s11, s81
	v_lshl_add_u64 v[168:169], s[64:65], 0, v[0:1]
	s_mov_b32 m0, s10
	ds_read_b128 v[180:183], v218 offset:16384
	ds_read_b128 v[184:187], v218 offset:17408
	ds_read_b128 v[188:191], v218 offset:18432
	ds_read_b128 v[192:195], v218 offset:19456
	ds_read_b128 v[196:199], v218 offset:20480
	ds_read_b128 v[200:203], v218 offset:21504
	ds_read_b128 v[220:223], v218 offset:22528
	ds_read_b128 v[224:227], v218 offset:23552
	global_load_lds_dwordx4 v[168:169], off
	s_add_i32 m0, s10, 0x2000
	s_add_u32 s90, s64, 0x40000
	v_lshl_add_u64 v[204:205], s[64:65], 0, v[170:171]
	s_addc_u32 s91, s65, 0
	s_add_i32 s9, s9, s81
	global_load_lds_dwordx4 v[204:205], off
	v_lshl_add_u64 v[228:229], s[90:91], 0, v[0:1]
	s_mov_b32 m0, s9
	v_lshl_add_u64 v[230:231], s[66:67], 0, v[160:161]
	global_load_lds_dwordx4 v[228:229], off
	v_lshl_add_u64 v[228:229], s[90:91], 0, v[170:171]
	s_add_i32 m0, s9, 0x2000
	s_nop 0
	global_load_lds_dwordx4 v[228:229], off
	v_lshl_add_u64 v[228:229], s[66:67], 0, v[158:159]
	s_mov_b32 m0, s61
	s_nop 0
	global_load_lds_dwordx4 v[228:229], off
	s_mov_b32 m0, s82
	s_nop 0
	global_load_lds_dwordx4 v[230:231], off
	s_waitcnt vmcnt(8)
	s_waitcnt lgkmcnt(0)
	s_barrier
; #define PG8_STAGE(bufoff, gbase, voff) do { _Pragma("unroll") for (int _i = 0; _i < 2; ++_i) \
;         __builtin_amdgcn_global_load_lds((const unsigned*)((const char*)(gbase) + (voff)[_i]), (PG8_LAS unsigned*)(lds + (bufoff) + ldsw + _i * 8192), 16, 0, 0); } while (0)
; #define PG8_LDA(dst, b, h) do { _Pragma("unroll") for (int m = 0; m < 4; ++m) _Pragma("unroll") for (int k = 0; k < 2; ++k) dst[m][k] = *(const PG8_LAS bf16x8*)(lds + PG8_SA(b, h) + aoff + m * 2048 + k * 1024); } while (0)
; #define PG8_LDB(dst, b, h) do { _Pragma("unroll") for (int n = 0; n < 2; ++n) _Pragma("unroll") for (int k = 0; k < 2; ++k) dst[n][k] = *(const PG8_LAS bf16x8*)(lds + PG8_SB(b, h) + boff + n * 2048 + k * 1024); } while (0)
; #define PG8_MMA(ai, bj, At, Bt) do { __builtin_amdgcn_s_setprio(1); _Pragma("unroll") for (int m = 0; m < 4; ++m) _Pragma("unroll") for (int n = 0; n < 2; ++n) _Pragma("unroll") for (int k = 0; k < 2; ++k) \
;         acc[ai][bj][m][n] = __builtin_amdgcn_mfma_f32_16x16x32_bf16(Bt[n][k], At[m][k], acc[ai][bj][m][n], 0, 0, 0); __builtin_amdgcn_s_setprio(0); } while (0)
; #define PG8_WAIT_V(n) asm volatile("s_waitcnt vmcnt(" #n ")" ::: "memory")
; #define PG8_WAIT_L(n) asm volatile("s_waitcnt lgkmcnt(" #n ")" ::: "memory")
; #define PG8_BAR __builtin_amdgcn_s_barrier()
; #define PG8_SCHED __builtin_amdgcn_sched_barrier(0)
; template <class Epi, class Sched>
; __device__ __forceinline__ void gemm_phase(PG8_LAS unsigned char* lds, const Gemm g, const Sched& S, const Epi& E) {
;     ...
;             PG8_WAIT_V(8); PG8_WAIT_L(0); PG8_BAR; PG8_MMA(1, 0, At, B0); PG8_MMA(1, 1, At, B1); PG8_BAR; PG8_SCHED;
;             PG8_LDB(B0, 1, 0); PG8_LDB(B1, 1, 1); PG8_SCHED; PG8_LDA(At, 1, 0); PG8_STAGE(PG8_SA(0, 1), a2 + hstepA, voffA);
;             PG8_WAIT_V(8); PG8_WAIT_L(0); PG8_BAR; PG8_MMA(0, 0, At, B0); PG8_MMA(0, 1, At, B1); PG8_BAR; PG8_SCHED;
	s_setprio 1
	s_waitcnt lgkmcnt(0)
	v_mfma_f32_16x16x32_bf16 v[94:97], v[130:133], v[180:183], v[94:97]
	v_mfma_f32_16x16x32_bf16 v[90:93], v[138:141], v[180:183], v[90:93]
	v_mfma_f32_16x16x32_bf16 v[86:89], v[130:133], v[188:191], v[86:89]
	v_mfma_f32_16x16x32_bf16 v[82:85], v[138:141], v[188:191], v[82:85]
	v_mfma_f32_16x16x32_bf16 v[78:81], v[130:133], v[196:199], v[78:81]
	v_mfma_f32_16x16x32_bf16 v[74:77], v[138:141], v[196:199], v[74:77]
	v_mfma_f32_16x16x32_bf16 v[70:73], v[130:133], v[220:223], v[70:73]
	v_mfma_f32_16x16x32_bf16 v[66:69], v[138:141], v[220:223], v[66:69]
	v_mfma_f32_16x16x32_bf16 v[94:97], v[134:137], v[184:187], v[94:97]
	v_mfma_f32_16x16x32_bf16 v[90:93], v[142:145], v[184:187], v[90:93]
	v_mfma_f32_16x16x32_bf16 v[86:89], v[134:137], v[192:195], v[86:89]
	v_mfma_f32_16x16x32_bf16 v[82:85], v[142:145], v[192:195], v[82:85]
	v_mfma_f32_16x16x32_bf16 v[78:81], v[134:137], v[200:203], v[78:81]
	v_mfma_f32_16x16x32_bf16 v[74:77], v[142:145], v[200:203], v[74:77]
	v_mfma_f32_16x16x32_bf16 v[70:73], v[134:137], v[224:227], v[70:73]
	v_mfma_f32_16x16x32_bf16 v[66:69], v[142:145], v[224:227], v[66:69]
	s_setprio 0
	s_setprio 1
	v_mfma_f32_16x16x32_bf16 v[30:33], v[146:149], v[180:183], v[30:33]
	v_mfma_f32_16x16x32_bf16 v[26:29], v[154:157], v[180:183], v[26:29]
	v_mfma_f32_16x16x32_bf16 v[22:25], v[146:149], v[188:191], v[22:25]
	v_mfma_f32_16x16x32_bf16 v[18:21], v[154:157], v[188:191], v[18:21]
	v_mfma_f32_16x16x32_bf16 v[14:17], v[146:149], v[196:199], v[14:17]
	v_mfma_f32_16x16x32_bf16 v[10:13], v[154:157], v[196:199], v[10:13]
	v_mfma_f32_16x16x32_bf16 v[6:9], v[146:149], v[220:223], v[6:9]
	v_mfma_f32_16x16x32_bf16 v[2:5], v[154:157], v[220:223], v[2:5]
	v_mfma_f32_16x16x32_bf16 v[30:33], v[150:153], v[184:187], v[30:33]
	v_mfma_f32_16x16x32_bf16 v[26:29], v[176:179], v[184:187], v[26:29]
	v_mfma_f32_16x16x32_bf16 v[22:25], v[150:153], v[192:195], v[22:25]
	v_mfma_f32_16x16x32_bf16 v[18:21], v[176:179], v[192:195], v[18:21]
	v_mfma_f32_16x16x32_bf16 v[14:17], v[150:153], v[200:203], v[14:17]
	v_mfma_f32_16x16x32_bf16 v[10:13], v[176:179], v[200:203], v[10:13]
	v_mfma_f32_16x16x32_bf16 v[6:9], v[150:153], v[224:227], v[6:9]
	v_mfma_f32_16x16x32_bf16 v[2:5], v[176:179], v[224:227], v[2:5]
	s_setprio 0
	s_barrier
	s_add_i32 s9, 0, 0x18000
	s_add_i32 s10, 0, 0x1c000
	v_add_u32_e32 v142, s9, v216
	v_add_u32_e32 v176, s10, v216
	ds_read_b128 v[130:133], v142
	ds_read_b128 v[134:137], v142 offset:1024
	ds_read_b128 v[138:141], v142 offset:2048
	ds_read_b128 v[142:145], v142 offset:3072
	ds_read_b128 v[146:149], v176
	ds_read_b128 v[150:153], v176 offset:1024
	ds_read_b128 v[154:157], v176 offset:2048
	ds_read_b128 v[176:179], v176 offset:3072
	s_add_u32 s66, s66, 0x40000
	s_addc_u32 s67, s67, 0
	s_mov_b32 m0, s83
	v_lshl_add_u64 v[232:233], s[66:67], 0, v[158:159]
	ds_read_b128 v[180:183], v218 offset:32768
	ds_read_b128 v[184:187], v218 offset:33792
	ds_read_b128 v[188:191], v218 offset:34816
	ds_read_b128 v[192:195], v218 offset:35840
	ds_read_b128 v[196:199], v218 offset:36864
	ds_read_b128 v[200:203], v218 offset:37888
	ds_read_b128 v[220:223], v218 offset:38912
	ds_read_b128 v[224:227], v218 offset:39936
	global_load_lds_dwordx4 v[232:233], off
	v_lshl_add_u64 v[232:233], s[66:67], 0, v[160:161]
	s_mov_b32 m0, s84
	s_nop 0
	global_load_lds_dwordx4 v[232:233], off
	s_waitcnt vmcnt(8)
	s_waitcnt lgkmcnt(0)
	s_barrier
	s_setprio 1
	s_waitcnt lgkmcnt(0)
	v_mfma_f32_16x16x32_bf16 v[126:129], v[130:133], v[180:183], v[126:129]
	v_mfma_f32_16x16x32_bf16 v[122:125], v[138:141], v[180:183], v[122:125]
	v_mfma_f32_16x16x32_bf16 v[118:121], v[130:133], v[188:191], v[118:121]
	v_mfma_f32_16x16x32_bf16 v[114:117], v[138:141], v[188:191], v[114:117]
	v_mfma_f32_16x16x32_bf16 v[110:113], v[130:133], v[196:199], v[110:113]
	v_mfma_f32_16x16x32_bf16 v[106:109], v[138:141], v[196:199], v[106:109]
	v_mfma_f32_16x16x32_bf16 v[102:105], v[130:133], v[220:223], v[102:105]
	v_mfma_f32_16x16x32_bf16 v[98:101], v[138:141], v[220:223], v[98:101]
	v_mfma_f32_16x16x32_bf16 v[126:129], v[134:137], v[184:187], v[126:129]
	v_mfma_f32_16x16x32_bf16 v[122:125], v[142:145], v[184:187], v[122:125]
	v_mfma_f32_16x16x32_bf16 v[118:121], v[134:137], v[192:195], v[118:121]
	v_mfma_f32_16x16x32_bf16 v[114:117], v[142:145], v[192:195], v[114:117]
	v_mfma_f32_16x16x32_bf16 v[110:113], v[134:137], v[200:203], v[110:113]
	v_mfma_f32_16x16x32_bf16 v[106:109], v[142:145], v[200:203], v[106:109]
	v_mfma_f32_16x16x32_bf16 v[102:105], v[134:137], v[224:227], v[102:105]
	v_mfma_f32_16x16x32_bf16 v[98:101], v[142:145], v[224:227], v[98:101]
	s_setprio 0
	s_setprio 1
	v_mfma_f32_16x16x32_bf16 v[62:65], v[146:149], v[180:183], v[62:65]
	v_mfma_f32_16x16x32_bf16 v[58:61], v[154:157], v[180:183], v[58:61]
	v_mfma_f32_16x16x32_bf16 v[54:57], v[146:149], v[188:191], v[54:57]
	v_mfma_f32_16x16x32_bf16 v[50:53], v[154:157], v[188:191], v[50:53]
	v_mfma_f32_16x16x32_bf16 v[46:49], v[146:149], v[196:199], v[46:49]
	v_mfma_f32_16x16x32_bf16 v[42:45], v[154:157], v[196:199], v[42:45]
	v_mfma_f32_16x16x32_bf16 v[38:41], v[146:149], v[220:223], v[38:41]
	v_mfma_f32_16x16x32_bf16 v[34:37], v[154:157], v[220:223], v[34:37]
	v_mfma_f32_16x16x32_bf16 v[62:65], v[150:153], v[184:187], v[62:65]
	v_mfma_f32_16x16x32_bf16 v[58:61], v[176:179], v[184:187], v[58:61]
	v_mfma_f32_16x16x32_bf16 v[54:57], v[150:153], v[192:195], v[54:57]
	v_mfma_f32_16x16x32_bf16 v[50:53], v[176:179], v[192:195], v[50:53]
	v_mfma_f32_16x16x32_bf16 v[46:49], v[150:153], v[200:203], v[46:49]
	v_mfma_f32_16x16x32_bf16 v[42:45], v[176:179], v[200:203], v[42:45]
	v_mfma_f32_16x16x32_bf16 v[38:41], v[150:153], v[224:227], v[38:41]
	v_mfma_f32_16x16x32_bf16 v[34:37], v[176:179], v[224:227], v[34:37]
	s_setprio 0
	s_barrier
; #define PG8_STAGE(bufoff, gbase, voff) do { _Pragma("unroll") for (int _i = 0; _i < 2; ++_i) \
;         __builtin_amdgcn_global_load_lds((const unsigned*)((const char*)(gbase) + (voff)[_i]), (PG8_LAS unsigned*)(lds + (bufoff) + ldsw + _i * 8192), 16, 0, 0); } while (0)
; #define PG8_LDA(dst, b, h) do { _Pragma("unroll") for (int m = 0; m < 4; ++m) _Pragma("unroll") for (int k = 0; k < 2; ++k) dst[m][k] = *(const PG8_LAS bf16x8*)(lds + PG8_SA(b, h) + aoff + m * 2048 + k * 1024); } while (0)
; #define PG8_LDB(dst, b, h) do { _Pragma("unroll") for (int n = 0; n < 2; ++n) _Pragma("unroll") for (int k = 0; k < 2; ++k) dst[n][k] = *(const PG8_LAS bf16x8*)(lds + PG8_SB(b, h) + boff + n * 2048 + k * 1024); } while (0)
; #define PG8_WAIT_V(n) asm volatile("s_waitcnt vmcnt(" #n ")" ::: "memory")
; template <class Epi, class Sched>
; __device__ __forceinline__ void gemm_phase(PG8_LAS unsigned char* lds, const Gemm g, const Sched& S, const Epi& E) {
;     ...
;         for (int t = 0; t < nt; t += 2) {
;             const bool last = (t == nt - 2);
;             const char* a1 = cA + (size_t)(t + 1) * kstep;
;             const char* a2 = last ? nA : cA + (size_t)(t + 2) * kstep; const char* b2 = last ? nB : cB + (size_t)(t + 2) * kstep;
;             const char* a3 = a2 + kstep; const char* b3 = b2 + kstep;
;             PG8_LDB(B0, 0, 0); PG8_LDB(B1, 0, 1); PG8_SCHED; PG8_LDA(At, 0, 0); PG8_STAGE(PG8_SA(1, 1), a1 + hstepA, voffA);
;             PG8_WAIT_V(8); PG8_WAIT_L(0); PG8_BAR; PG8_MMA(0, 0, At, B0); PG8_MMA(0, 1, At, B1); PG8_BAR; PG8_SCHED;
;             PG8_LDA(At, 0, 1); PG8_STAGE(PG8_SB(0, 0), b2, voffB); PG8_STAGE(PG8_SB(0, 1), b2 + hstepB, voffB); PG8_STAGE(PG8_SA(0, 0), a2, voffA);
;             PG8_WAIT_V(8); PG8_WAIT_L(0); PG8_BAR; PG8_MMA(1, 0, At, B0); PG8_MMA(1, 1, At, B1); PG8_BAR; PG8_SCHED;
;             PG8_LDB(B0, 1, 0); PG8_LDB(B1, 1, 1); PG8_SCHED; PG8_LDA(At, 1, 0); PG8_STAGE(PG8_SA(0, 1), a2 + hstepA, voffA);
;             PG8_WAIT_V(8); PG8_WAIT_L(0); PG8_BAR; PG8_MMA(0, 0, At, B0); PG8_MMA(0, 1, At, B1); PG8_BAR; PG8_SCHED;
;             PG8_LDA(At, 1, 1); PG8_STAGE(PG8_SB(1, 0), b3, voffB); PG8_STAGE(PG8_SB(1, 1), b3 + hstepB, voffB); PG8_STAGE(PG8_SA(1, 0), a3, voffA);
;             PG8_WAIT_V(8); PG8_WAIT_L(0); PG8_BAR; PG8_MMA(1, 0, At, B0); PG8_MMA(1, 1, At, B1); PG8_BAR; PG8_SCHED;
;         }
;         if (wr == 0) PG8_BAR;
	s_add_i32 s9, s9, s81
	v_lshl_add_u64 v[168:169], v[168:169], 0, s[22:23]
	s_mov_b32 m0, s9
	ds_read_b128 v[180:183], v218 offset:49152
	ds_read_b128 v[184:187], v218 offset:50176
	ds_read_b128 v[188:191], v218 offset:51200
	ds_read_b128 v[192:195], v218 offset:52224
	ds_read_b128 v[196:199], v218 offset:53248
	ds_read_b128 v[200:203], v218 offset:54272
	ds_read_b128 v[220:223], v218 offset:55296
	ds_read_b128 v[224:227], v218 offset:56320
	global_load_lds_dwordx4 v[168:169], off
	s_add_i32 m0, s9, 0x2000
	s_add_u32 s64, s64, 0x40080
	v_lshl_add_u64 v[168:169], v[204:205], 0, s[22:23]
	s_addc_u32 s65, s65, 0
	s_add_i32 s9, s10, s81
	global_load_lds_dwordx4 v[168:169], off
	v_lshl_add_u64 v[168:169], s[64:65], 0, v[0:1]
	s_mov_b32 m0, s9
	s_nop 0
	global_load_lds_dwordx4 v[168:169], off
	v_lshl_add_u64 v[168:169], s[64:65], 0, v[170:171]
	s_add_i32 m0, s9, 0x2000
	s_nop 0
	global_load_lds_dwordx4 v[168:169], off
	v_lshl_add_u64 v[168:169], v[228:229], 0, s[22:23]
	s_mov_b32 m0, s20
	s_nop 0
	global_load_lds_dwordx4 v[168:169], off
	v_lshl_add_u64 v[168:169], v[230:231], 0, s[22:23]
	s_mov_b32 m0, s85
	s_nop 0
	global_load_lds_dwordx4 v[168:169], off
	s_waitcnt vmcnt(8)
	s_waitcnt lgkmcnt(0)
	s_barrier
	s_setprio 1
	s_waitcnt lgkmcnt(0)
	v_mfma_f32_16x16x32_bf16 v[94:97], v[130:133], v[180:183], v[94:97]
	v_mfma_f32_16x16x32_bf16 v[90:93], v[138:141], v[180:183], v[90:93]
	v_mfma_f32_16x16x32_bf16 v[86:89], v[130:133], v[188:191], v[86:89]
	v_mfma_f32_16x16x32_bf16 v[82:85], v[138:141], v[188:191], v[82:85]
	v_mfma_f32_16x16x32_bf16 v[78:81], v[130:133], v[196:199], v[78:81]
	v_mfma_f32_16x16x32_bf16 v[74:77], v[138:141], v[196:199], v[74:77]
	v_mfma_f32_16x16x32_bf16 v[70:73], v[130:133], v[220:223], v[70:73]
	v_mfma_f32_16x16x32_bf16 v[66:69], v[138:141], v[220:223], v[66:69]
	v_mfma_f32_16x16x32_bf16 v[94:97], v[134:137], v[184:187], v[94:97]
	v_mfma_f32_16x16x32_bf16 v[90:93], v[142:145], v[184:187], v[90:93]
	v_mfma_f32_16x16x32_bf16 v[86:89], v[134:137], v[192:195], v[86:89]
	v_mfma_f32_16x16x32_bf16 v[82:85], v[142:145], v[192:195], v[82:85]
	v_mfma_f32_16x16x32_bf16 v[78:81], v[134:137], v[200:203], v[78:81]
	v_mfma_f32_16x16x32_bf16 v[74:77], v[142:145], v[200:203], v[74:77]
	v_mfma_f32_16x16x32_bf16 v[70:73], v[134:137], v[224:227], v[70:73]
	v_mfma_f32_16x16x32_bf16 v[66:69], v[142:145], v[224:227], v[66:69]
	s_setprio 0
	s_setprio 1
	v_mfma_f32_16x16x32_bf16 v[30:33], v[146:149], v[180:183], v[30:33]
	v_mfma_f32_16x16x32_bf16 v[26:29], v[154:157], v[180:183], v[26:29]
	s_add_i32 s8, s8, 2
	v_mfma_f32_16x16x32_bf16 v[22:25], v[146:149], v[188:191], v[22:25]
	s_add_u32 s28, s28, 0x100
	v_mfma_f32_16x16x32_bf16 v[18:21], v[154:157], v[188:191], v[18:21]
	s_addc_u32 s29, s29, 0
	v_mfma_f32_16x16x32_bf16 v[14:17], v[146:149], v[196:199], v[14:17]
	s_add_u32 s7, s7, 0x100
	v_mfma_f32_16x16x32_bf16 v[10:13], v[154:157], v[196:199], v[10:13]
	s_addc_u32 s88, s88, 0
	v_mfma_f32_16x16x32_bf16 v[6:9], v[146:149], v[220:223], v[6:9]
	s_add_u32 s9, s28, 0xfffc0080
	v_mfma_f32_16x16x32_bf16 v[2:5], v[154:157], v[220:223], v[2:5]
	s_addc_u32 s10, s29, -1
	v_mfma_f32_16x16x32_bf16 v[30:33], v[150:153], v[184:187], v[30:33]
	s_add_i32 s11, 0, 0x10000
	v_mfma_f32_16x16x32_bf16 v[26:29], v[176:179], v[184:187], v[26:29]
	s_cmp_eq_u32 s8, 12
	v_mfma_f32_16x16x32_bf16 v[22:25], v[150:153], v[192:195], v[22:25]
	s_cselect_b32 s67, s5, s10
	v_mfma_f32_16x16x32_bf16 v[18:21], v[176:179], v[192:195], v[18:21]
	s_cselect_b32 s66, s45, s9
	v_mfma_f32_16x16x32_bf16 v[14:17], v[150:153], v[200:203], v[14:17]
	s_cselect_b32 s65, s43, s88
	v_mfma_f32_16x16x32_bf16 v[10:13], v[176:179], v[200:203], v[10:13]
	s_cselect_b32 s64, s6, s7
	v_mfma_f32_16x16x32_bf16 v[6:9], v[150:153], v[224:227], v[6:9]
	s_add_i32 s9, 0, 0x14000
	v_mfma_f32_16x16x32_bf16 v[2:5], v[176:179], v[224:227], v[2:5]
	s_cmp_gt_u32 s8, 13
	s_setprio 0
	s_barrier
	s_cbranch_scc0 .Lrot_197
	s_and_b64 vcc, exec, s[38:39]
	s_cbranch_vccz .LBB0_200
	s_barrier

; #define PG8_STAGE(bufoff, gbase, voff) do { _Pragma("unroll") for (int _i = 0; _i < 2; ++_i) \
;         __builtin_amdgcn_global_load_lds((const unsigned*)((const char*)(gbase) + (voff)[_i]), (PG8_LAS unsigned*)(lds + (bufoff) + ldsw + _i * 8192), 16, 0, 0); } while (0)
; #define PG8_LDA(dst, b, h) do { _Pragma("unroll") for (int m = 0; m < 4; ++m) _Pragma("unroll") for (int k = 0; k < 2; ++k) dst[m][k] = *(const PG8_LAS bf16x8*)(lds + PG8_SA(b, h) + aoff + m * 2048 + k * 1024); } while (0)
; #define PG8_LDB(dst, b, h) do { _Pragma("unroll") for (int n = 0; n < 2; ++n) _Pragma("unroll") for (int k = 0; k < 2; ++k) dst[n][k] = *(const PG8_LAS bf16x8*)(lds + PG8_SB(b, h) + boff + n * 2048 + k * 1024); } while (0)
; #define PG8_MMA(ai, bj, At, Bt) do { __builtin_amdgcn_s_setprio(1); _Pragma("unroll") for (int m = 0; m < 4; ++m) _Pragma("unroll") for (int n = 0; n < 2; ++n) _Pragma("unroll") for (int k = 0; k < 2; ++k) \
;         acc[ai][bj][m][n] = __builtin_amdgcn_mfma_f32_16x16x32_bf16(Bt[n][k], At[m][k], acc[ai][bj][m][n], 0, 0, 0); __builtin_amdgcn_s_setprio(0); } while (0)
; #define PG8_WAIT_V(n) asm volatile("s_waitcnt vmcnt(" #n ")" ::: "memory")
; #define PG8_WAIT_L(n) asm volatile("s_waitcnt lgkmcnt(" #n ")" ::: "memory")
; #define PG8_BAR __builtin_amdgcn_s_barrier()
; #define PG8_SCHED __builtin_amdgcn_sched_barrier(0)
; template <class Epi, class Sched>
; __device__ __forceinline__ void gemm_phase(PG8_LAS unsigned char* lds, const Gemm g, const Sched& S, const Epi& E) {
;     ...
;         for (int t = 0; t < nt; t += 2) {
;             const bool last = (t == nt - 2);
;             const char* a1 = cA + (size_t)(t + 1) * kstep;
;             const char* a2 = last ? nA : cA + (size_t)(t + 2) * kstep; const char* b2 = last ? nB : cB + (size_t)(t + 2) * kstep;
;             const char* a3 = a2 + kstep; const char* b3 = b2 + kstep;
;             PG8_LDB(B0, 0, 0); PG8_LDB(B1, 0, 1); PG8_SCHED; PG8_LDA(At, 0, 0); PG8_STAGE(PG8_SA(1, 1), a1 + hstepA, voffA);
;             PG8_WAIT_V(8); PG8_WAIT_L(0); PG8_BAR; PG8_MMA(0, 0, At, B0); PG8_MMA(0, 1, At, B1); PG8_BAR; PG8_SCHED;
;             PG8_LDA(At, 0, 1); PG8_STAGE(PG8_SB(0, 0), b2, voffB); PG8_STAGE(PG8_SB(0, 1), b2 + hstepB, voffB); PG8_STAGE(PG8_SA(0, 0), a2, voffA);
;             PG8_WAIT_V(8); PG8_WAIT_L(0); PG8_BAR; PG8_MMA(1, 0, At, B0); PG8_MMA(1, 1, At, B1); PG8_BAR; PG8_SCHED;
.LBB0_277:
	s_add_u32 s9, s28, 0xfff80080
	s_addc_u32 s10, s29, -1
	s_add_i32 s11, 0, 0x10000
	s_cmp_eq_u32 s8, 28
	s_cselect_b32 vcc_hi, s4, s10
	s_cselect_b32 vcc_lo, s5, s9
	s_cselect_b32 s45, s13, s15
	s_cselect_b32 s44, s6, s7
	s_add_i32 s9, 0, 0x14000
.Lrot_277:
	v_add_u32_e32 v0, s11, v182
	ds_read_b128 v[130:133], v0
	ds_read_b128 v[148:151], v0 offset:1024
	ds_read_b128 v[152:155], v0 offset:2048
	ds_read_b128 v[156:159], v0 offset:3072
	v_add_u32_e32 v0, s9, v182
	ds_read_b128 v[170:173], v0
	ds_read_b128 v[174:177], v0 offset:1024
	ds_read_b128 v[178:181], v0 offset:2048
	ds_read_b128 v[202:205], v0 offset:3072
	v_lshl_add_u64 v[160:161], s[28:29], 0, v[144:145]
	s_add_i32 m0, s39, 0xc000
	ds_read_b128 v[216:219], v200
	ds_read_b128 v[220:223], v200 offset:1024
	ds_read_b128 v[224:227], v200 offset:2048
	ds_read_b128 v[228:231], v200 offset:3072
	ds_read_b128 v[232:235], v200 offset:4096
	ds_read_b128 v[236:239], v200 offset:5120
	ds_read_b128 v[240:243], v200 offset:6144
	ds_read_b128 v[244:247], v200 offset:7168
	global_load_lds_dwordx4 v[160:161], off
	v_lshl_add_u64 v[160:161], s[28:29], 0, v[146:147]
	s_add_i32 m0, s39, 0xe000
	s_nop 0
	global_load_lds_dwordx4 v[160:161], off
	s_waitcnt vmcnt(8)
	s_waitcnt lgkmcnt(0)
	s_barrier
	s_setprio 1
	s_waitcnt lgkmcnt(0)
	v_mfma_f32_16x16x32_bf16 v[126:129], v[130:133], v[216:219], v[126:129]
	v_mfma_f32_16x16x32_bf16 v[122:125], v[152:155], v[216:219], v[122:125]
	v_mfma_f32_16x16x32_bf16 v[110:113], v[130:133], v[224:227], v[110:113]
	v_mfma_f32_16x16x32_bf16 v[106:109], v[152:155], v[224:227], v[106:109]
	v_mfma_f32_16x16x32_bf16 v[94:97], v[130:133], v[232:235], v[94:97]
	v_mfma_f32_16x16x32_bf16 v[90:93], v[152:155], v[232:235], v[90:93]
	v_mfma_f32_16x16x32_bf16 v[78:81], v[130:133], v[240:243], v[78:81]
	v_mfma_f32_16x16x32_bf16 v[74:77], v[152:155], v[240:243], v[74:77]
	v_mfma_f32_16x16x32_bf16 v[126:129], v[148:151], v[220:223], v[126:129]
	v_mfma_f32_16x16x32_bf16 v[122:125], v[156:159], v[220:223], v[122:125]
	v_mfma_f32_16x16x32_bf16 v[110:113], v[148:151], v[228:231], v[110:113]
	v_mfma_f32_16x16x32_bf16 v[106:109], v[156:159], v[228:231], v[106:109]
	v_mfma_f32_16x16x32_bf16 v[94:97], v[148:151], v[236:239], v[94:97]
	v_mfma_f32_16x16x32_bf16 v[90:93], v[156:159], v[236:239], v[90:93]
	v_mfma_f32_16x16x32_bf16 v[78:81], v[148:151], v[244:247], v[78:81]
	v_mfma_f32_16x16x32_bf16 v[74:77], v[156:159], v[244:247], v[74:77]
	s_setprio 0
	s_setprio 1
	v_mfma_f32_16x16x32_bf16 v[118:121], v[170:173], v[216:219], v[118:121]
	v_mfma_f32_16x16x32_bf16 v[114:117], v[178:181], v[216:219], v[114:117]
	v_mfma_f32_16x16x32_bf16 v[102:105], v[170:173], v[224:227], v[102:105]
	v_mfma_f32_16x16x32_bf16 v[98:101], v[178:181], v[224:227], v[98:101]
	v_mfma_f32_16x16x32_bf16 v[86:89], v[170:173], v[232:235], v[86:89]
	v_mfma_f32_16x16x32_bf16 v[82:85], v[178:181], v[232:235], v[82:85]
	v_mfma_f32_16x16x32_bf16 v[70:73], v[170:173], v[240:243], v[70:73]
	v_mfma_f32_16x16x32_bf16 v[66:69], v[178:181], v[240:243], v[66:69]
	v_mfma_f32_16x16x32_bf16 v[118:121], v[174:177], v[220:223], v[118:121]
	v_mfma_f32_16x16x32_bf16 v[114:117], v[202:205], v[220:223], v[114:117]
	v_mfma_f32_16x16x32_bf16 v[102:105], v[174:177], v[228:231], v[102:105]
	v_mfma_f32_16x16x32_bf16 v[98:101], v[202:205], v[228:231], v[98:101]
	v_mfma_f32_16x16x32_bf16 v[86:89], v[174:177], v[236:239], v[86:89]
	v_mfma_f32_16x16x32_bf16 v[82:85], v[202:205], v[236:239], v[82:85]
	v_mfma_f32_16x16x32_bf16 v[70:73], v[174:177], v[244:247], v[70:73]
	v_mfma_f32_16x16x32_bf16 v[66:69], v[202:205], v[244:247], v[66:69]
	s_setprio 0
	s_barrier
	s_add_i32 s10, s11, s20
	v_lshl_add_u64 v[160:161], s[44:45], 0, v[136:137]
	s_mov_b32 m0, s10
	ds_read_b128 v[216:219], v200 offset:16384
	ds_read_b128 v[220:223], v200 offset:17408
	ds_read_b128 v[224:227], v200 offset:18432
	ds_read_b128 v[228:231], v200 offset:19456
	ds_read_b128 v[232:235], v200 offset:20480
	ds_read_b128 v[236:239], v200 offset:21504
	ds_read_b128 v[240:243], v200 offset:22528
	ds_read_b128 v[244:247], v200 offset:23552
	global_load_lds_dwordx4 v[160:161], off
	s_add_i32 m0, s10, 0x2000
	s_add_u32 s90, s44, 0x80000
	v_lshl_add_u64 v[248:249], s[44:45], 0, v[140:141]
	s_addc_u32 s91, s45, 0
	s_add_i32 s9, s9, s20
	global_load_lds_dwordx4 v[248:249], off
	v_lshl_add_u64 v[250:251], s[90:91], 0, v[136:137]
	s_mov_b32 m0, s9
	v_lshl_add_u64 v[252:253], vcc, 0, v[138:139]
	global_load_lds_dwordx4 v[250:251], off
	v_lshl_add_u64 v[250:251], s[90:91], 0, v[140:141]
	s_add_i32 m0, s9, 0x2000
	s_nop 0
	global_load_lds_dwordx4 v[250:251], off
	v_lshl_add_u64 v[250:251], vcc, 0, v[134:135]
	s_mov_b32 m0, s39
	s_nop 0
	global_load_lds_dwordx4 v[250:251], off
	s_mov_b32 m0, s69
	s_nop 0
	global_load_lds_dwordx4 v[252:253], off
	s_waitcnt vmcnt(8)
	s_waitcnt lgkmcnt(0)
	s_barrier
; #define PG8_STAGE(bufoff, gbase, voff) do { _Pragma("unroll") for (int _i = 0; _i < 2; ++_i) \
;         __builtin_amdgcn_global_load_lds((const unsigned*)((const char*)(gbase) + (voff)[_i]), (PG8_LAS unsigned*)(lds + (bufoff) + ldsw + _i * 8192), 16, 0, 0); } while (0)
; #define PG8_LDA(dst, b, h) do { _Pragma("unroll") for (int m = 0; m < 4; ++m) _Pragma("unroll") for (int k = 0; k < 2; ++k) dst[m][k] = *(const PG8_LAS bf16x8*)(lds + PG8_SA(b, h) + aoff + m * 2048 + k * 1024); } while (0)
; #define PG8_LDB(dst, b, h) do { _Pragma("unroll") for (int n = 0; n < 2; ++n) _Pragma("unroll") for (int k = 0; k < 2; ++k) dst[n][k] = *(const PG8_LAS bf16x8*)(lds + PG8_SB(b, h) + boff + n * 2048 + k * 1024); } while (0)
; #define PG8_MMA(ai, bj, At, Bt) do { __builtin_amdgcn_s_setprio(1); _Pragma("unroll") for (int m = 0; m < 4; ++m) _Pragma("unroll") for (int n = 0; n < 2; ++n) _Pragma("unroll") for (int k = 0; k < 2; ++k) \
;         acc[ai][bj][m][n] = __builtin_amdgcn_mfma_f32_16x16x32_bf16(Bt[n][k], At[m][k], acc[ai][bj][m][n], 0, 0, 0); __builtin_amdgcn_s_setprio(0); } while (0)
; #define PG8_WAIT_V(n) asm volatile("s_waitcnt vmcnt(" #n ")" ::: "memory")
; #define PG8_WAIT_L(n) asm volatile("s_waitcnt lgkmcnt(" #n ")" ::: "memory")
; #define PG8_BAR __builtin_amdgcn_s_barrier()
; #define PG8_SCHED __builtin_amdgcn_sched_barrier(0)
; template <class Epi, class Sched>
; __device__ __forceinline__ void gemm_phase(PG8_LAS unsigned char* lds, const Gemm g, const Sched& S, const Epi& E) {
;     ...
;             PG8_WAIT_V(8); PG8_WAIT_L(0); PG8_BAR; PG8_MMA(1, 0, At, B0); PG8_MMA(1, 1, At, B1); PG8_BAR; PG8_SCHED;
;             PG8_LDB(B0, 1, 0); PG8_LDB(B1, 1, 1); PG8_SCHED; PG8_LDA(At, 1, 0); PG8_STAGE(PG8_SA(0, 1), a2 + hstepA, voffA);
;             PG8_WAIT_V(8); PG8_WAIT_L(0); PG8_BAR; PG8_MMA(0, 0, At, B0); PG8_MMA(0, 1, At, B1); PG8_BAR; PG8_SCHED;
	s_setprio 1
	s_waitcnt lgkmcnt(0)
	v_mfma_f32_16x16x32_bf16 v[62:65], v[130:133], v[216:219], v[62:65]
	v_mfma_f32_16x16x32_bf16 v[58:61], v[152:155], v[216:219], v[58:61]
	v_mfma_f32_16x16x32_bf16 v[46:49], v[130:133], v[224:227], v[46:49]
	v_mfma_f32_16x16x32_bf16 v[42:45], v[152:155], v[224:227], v[42:45]
	v_mfma_f32_16x16x32_bf16 v[30:33], v[130:133], v[232:235], v[30:33]
	v_mfma_f32_16x16x32_bf16 v[26:29], v[152:155], v[232:235], v[26:29]
	v_mfma_f32_16x16x32_bf16 v[14:17], v[130:133], v[240:243], v[14:17]
	v_mfma_f32_16x16x32_bf16 v[10:13], v[152:155], v[240:243], v[10:13]
	v_mfma_f32_16x16x32_bf16 v[62:65], v[148:151], v[220:223], v[62:65]
	v_mfma_f32_16x16x32_bf16 v[58:61], v[156:159], v[220:223], v[58:61]
	v_mfma_f32_16x16x32_bf16 v[46:49], v[148:151], v[228:231], v[46:49]
	v_mfma_f32_16x16x32_bf16 v[42:45], v[156:159], v[228:231], v[42:45]
	v_mfma_f32_16x16x32_bf16 v[30:33], v[148:151], v[236:239], v[30:33]
	v_mfma_f32_16x16x32_bf16 v[26:29], v[156:159], v[236:239], v[26:29]
	v_mfma_f32_16x16x32_bf16 v[14:17], v[148:151], v[244:247], v[14:17]
	v_mfma_f32_16x16x32_bf16 v[10:13], v[156:159], v[244:247], v[10:13]
	s_setprio 0
	s_setprio 1
	v_mfma_f32_16x16x32_bf16 v[54:57], v[170:173], v[216:219], v[54:57]
	v_mfma_f32_16x16x32_bf16 v[50:53], v[178:181], v[216:219], v[50:53]
	v_mfma_f32_16x16x32_bf16 v[38:41], v[170:173], v[224:227], v[38:41]
	v_mfma_f32_16x16x32_bf16 v[34:37], v[178:181], v[224:227], v[34:37]
	v_mfma_f32_16x16x32_bf16 v[22:25], v[170:173], v[232:235], v[22:25]
	v_mfma_f32_16x16x32_bf16 v[18:21], v[178:181], v[232:235], v[18:21]
	v_mfma_f32_16x16x32_bf16 v[6:9], v[170:173], v[240:243], v[6:9]
	v_mfma_f32_16x16x32_bf16 v[2:5], v[178:181], v[240:243], v[2:5]
	v_mfma_f32_16x16x32_bf16 v[54:57], v[174:177], v[220:223], v[54:57]
	v_mfma_f32_16x16x32_bf16 v[50:53], v[202:205], v[220:223], v[50:53]
	v_mfma_f32_16x16x32_bf16 v[38:41], v[174:177], v[228:231], v[38:41]
	v_mfma_f32_16x16x32_bf16 v[34:37], v[202:205], v[228:231], v[34:37]
	v_mfma_f32_16x16x32_bf16 v[22:25], v[174:177], v[236:239], v[22:25]
	v_mfma_f32_16x16x32_bf16 v[18:21], v[202:205], v[236:239], v[18:21]
	v_mfma_f32_16x16x32_bf16 v[6:9], v[174:177], v[244:247], v[6:9]
	v_mfma_f32_16x16x32_bf16 v[2:5], v[202:205], v[244:247], v[2:5]
	s_setprio 0
	s_barrier
	s_add_i32 s9, 0, 0x18000
	v_add_u32_e32 v0, s9, v182
	s_add_i32 s10, 0, 0x1c000
	ds_read_b128 v[130:133], v0
	ds_read_b128 v[148:151], v0 offset:1024
	ds_read_b128 v[152:155], v0 offset:2048
	ds_read_b128 v[156:159], v0 offset:3072
	v_add_u32_e32 v0, s10, v182
	ds_read_b128 v[170:173], v0
	ds_read_b128 v[174:177], v0 offset:1024
	ds_read_b128 v[178:181], v0 offset:2048
	ds_read_b128 v[202:205], v0 offset:3072
	s_add_u32 s90, vcc_lo, 0x80000
	s_addc_u32 s91, vcc_hi, 0
	s_mov_b32 m0, s80
	v_lshl_add_u64 v[168:169], s[90:91], 0, v[134:135]
	ds_read_b128 v[216:219], v200 offset:32768
	ds_read_b128 v[220:223], v200 offset:33792
	ds_read_b128 v[224:227], v200 offset:34816
	ds_read_b128 v[228:231], v200 offset:35840
	ds_read_b128 v[232:235], v200 offset:36864
	ds_read_b128 v[236:239], v200 offset:37888
	ds_read_b128 v[240:243], v200 offset:38912
	ds_read_b128 v[244:247], v200 offset:39936
	global_load_lds_dwordx4 v[168:169], off
	v_lshl_add_u64 v[168:169], s[90:91], 0, v[138:139]
	s_mov_b32 m0, s81
	s_nop 0
	global_load_lds_dwordx4 v[168:169], off
	s_waitcnt vmcnt(8)
	s_waitcnt lgkmcnt(0)
	s_barrier
	s_setprio 1
	s_waitcnt lgkmcnt(0)
	v_mfma_f32_16x16x32_bf16 v[126:129], v[130:133], v[216:219], v[126:129]
	v_mfma_f32_16x16x32_bf16 v[122:125], v[152:155], v[216:219], v[122:125]
	v_mfma_f32_16x16x32_bf16 v[110:113], v[130:133], v[224:227], v[110:113]
	v_mfma_f32_16x16x32_bf16 v[106:109], v[152:155], v[224:227], v[106:109]
	v_mfma_f32_16x16x32_bf16 v[94:97], v[130:133], v[232:235], v[94:97]
	v_mfma_f32_16x16x32_bf16 v[90:93], v[152:155], v[232:235], v[90:93]
	v_mfma_f32_16x16x32_bf16 v[78:81], v[130:133], v[240:243], v[78:81]
	v_mfma_f32_16x16x32_bf16 v[74:77], v[152:155], v[240:243], v[74:77]
	v_mfma_f32_16x16x32_bf16 v[126:129], v[148:151], v[220:223], v[126:129]
	v_mfma_f32_16x16x32_bf16 v[122:125], v[156:159], v[220:223], v[122:125]
	v_mfma_f32_16x16x32_bf16 v[110:113], v[148:151], v[228:231], v[110:113]
	v_mfma_f32_16x16x32_bf16 v[106:109], v[156:159], v[228:231], v[106:109]
	v_mfma_f32_16x16x32_bf16 v[94:97], v[148:151], v[236:239], v[94:97]
	v_mfma_f32_16x16x32_bf16 v[90:93], v[156:159], v[236:239], v[90:93]
	v_mfma_f32_16x16x32_bf16 v[78:81], v[148:151], v[244:247], v[78:81]
	v_mfma_f32_16x16x32_bf16 v[74:77], v[156:159], v[244:247], v[74:77]
	s_setprio 0
	s_setprio 1
	v_mfma_f32_16x16x32_bf16 v[118:121], v[170:173], v[216:219], v[118:121]
	v_mfma_f32_16x16x32_bf16 v[114:117], v[178:181], v[216:219], v[114:117]
	v_mfma_f32_16x16x32_bf16 v[102:105], v[170:173], v[224:227], v[102:105]
	v_mfma_f32_16x16x32_bf16 v[98:101], v[178:181], v[224:227], v[98:101]
	v_mfma_f32_16x16x32_bf16 v[86:89], v[170:173], v[232:235], v[86:89]
	v_mfma_f32_16x16x32_bf16 v[82:85], v[178:181], v[232:235], v[82:85]
	v_mfma_f32_16x16x32_bf16 v[70:73], v[170:173], v[240:243], v[70:73]
	v_mfma_f32_16x16x32_bf16 v[66:69], v[178:181], v[240:243], v[66:69]
	v_mfma_f32_16x16x32_bf16 v[118:121], v[174:177], v[220:223], v[118:121]
	v_mfma_f32_16x16x32_bf16 v[114:117], v[202:205], v[220:223], v[114:117]
	v_mfma_f32_16x16x32_bf16 v[102:105], v[174:177], v[228:231], v[102:105]
	v_mfma_f32_16x16x32_bf16 v[98:101], v[202:205], v[228:231], v[98:101]
	v_mfma_f32_16x16x32_bf16 v[86:89], v[174:177], v[236:239], v[86:89]
	v_mfma_f32_16x16x32_bf16 v[82:85], v[202:205], v[236:239], v[82:85]
	v_mfma_f32_16x16x32_bf16 v[70:73], v[174:177], v[244:247], v[70:73]
	v_mfma_f32_16x16x32_bf16 v[66:69], v[202:205], v[244:247], v[66:69]
	s_setprio 0
	s_barrier
; #define PG8_STAGE(bufoff, gbase, voff) do { _Pragma("unroll") for (int _i = 0; _i < 2; ++_i) \
;         __builtin_amdgcn_global_load_lds((const unsigned*)((const char*)(gbase) + (voff)[_i]), (PG8_LAS unsigned*)(lds + (bufoff) + ldsw + _i * 8192), 16, 0, 0); } while (0)
; #define PG8_LDA(dst, b, h) do { _Pragma("unroll") for (int m = 0; m < 4; ++m) _Pragma("unroll") for (int k = 0; k < 2; ++k) dst[m][k] = *(const PG8_LAS bf16x8*)(lds + PG8_SA(b, h) + aoff + m * 2048 + k * 1024); } while (0)
; #define PG8_LDB(dst, b, h) do { _Pragma("unroll") for (int n = 0; n < 2; ++n) _Pragma("unroll") for (int k = 0; k < 2; ++k) dst[n][k] = *(const PG8_LAS bf16x8*)(lds + PG8_SB(b, h) + boff + n * 2048 + k * 1024); } while (0)
; #define PG8_WAIT_V(n) asm volatile("s_waitcnt vmcnt(" #n ")" ::: "memory")
; #define PG8_BAR __builtin_amdgcn_s_barrier()
; template <class Epi, class Sched>
; __device__ __forceinline__ void gemm_phase(PG8_LAS unsigned char* lds, const Gemm g, const Sched& S, const Epi& E) {
;     ...
;         for (int t = 0; t < nt; t += 2) {
;             const bool last = (t == nt - 2);
;             const char* a1 = cA + (size_t)(t + 1) * kstep;
;             const char* a2 = last ? nA : cA + (size_t)(t + 2) * kstep; const char* b2 = last ? nB : cB + (size_t)(t + 2) * kstep;
;             const char* a3 = a2 + kstep; const char* b3 = b2 + kstep;
;             PG8_LDB(B0, 0, 0); PG8_LDB(B1, 0, 1); PG8_SCHED; PG8_LDA(At, 0, 0); PG8_STAGE(PG8_SA(1, 1), a1 + hstepA, voffA);
;             PG8_WAIT_V(8); PG8_WAIT_L(0); PG8_BAR; PG8_MMA(0, 0, At, B0); PG8_MMA(0, 1, At, B1); PG8_BAR; PG8_SCHED;
;             PG8_LDA(At, 0, 1); PG8_STAGE(PG8_SB(0, 0), b2, voffB); PG8_STAGE(PG8_SB(0, 1), b2 + hstepB, voffB); PG8_STAGE(PG8_SA(0, 0), a2, voffA);
;             PG8_WAIT_V(8); PG8_WAIT_L(0); PG8_BAR; PG8_MMA(1, 0, At, B0); PG8_MMA(1, 1, At, B1); PG8_BAR; PG8_SCHED;
;             PG8_LDB(B0, 1, 0); PG8_LDB(B1, 1, 1); PG8_SCHED; PG8_LDA(At, 1, 0); PG8_STAGE(PG8_SA(0, 1), a2 + hstepA, voffA);
;             PG8_WAIT_V(8); PG8_WAIT_L(0); PG8_BAR; PG8_MMA(0, 0, At, B0); PG8_MMA(0, 1, At, B1); PG8_BAR; PG8_SCHED;
;             PG8_LDA(At, 1, 1); PG8_STAGE(PG8_SB(1, 0), b3, voffB); PG8_STAGE(PG8_SB(1, 1), b3 + hstepB, voffB); PG8_STAGE(PG8_SA(1, 0), a3, voffA);
;             PG8_WAIT_V(8); PG8_WAIT_L(0); PG8_BAR; PG8_MMA(1, 0, At, B0); PG8_MMA(1, 1, At, B1); PG8_BAR; PG8_SCHED;
	s_add_i32 s9, s9, s20
	v_lshl_add_u64 v[160:161], v[160:161], 0, s[22:23]
	s_mov_b32 m0, s9
	ds_read_b128 v[216:219], v200 offset:49152
	ds_read_b128 v[220:223], v200 offset:50176
	ds_read_b128 v[224:227], v200 offset:51200
	ds_read_b128 v[228:231], v200 offset:52224
	ds_read_b128 v[232:235], v200 offset:53248
	ds_read_b128 v[236:239], v200 offset:54272
	ds_read_b128 v[240:243], v200 offset:55296
	ds_read_b128 v[244:247], v200 offset:56320
	global_load_lds_dwordx4 v[160:161], off
	s_add_i32 m0, s9, 0x2000
	s_add_u32 s44, s44, 0x80080
	v_lshl_add_u64 v[160:161], v[248:249], 0, s[22:23]
	s_addc_u32 s45, s45, 0
	s_add_i32 s9, s10, s20
	global_load_lds_dwordx4 v[160:161], off
	v_lshl_add_u64 v[160:161], s[44:45], 0, v[136:137]
	s_mov_b32 m0, s9
	s_nop 0
	global_load_lds_dwordx4 v[160:161], off
	v_lshl_add_u64 v[160:161], s[44:45], 0, v[140:141]
	s_add_i32 m0, s9, 0x2000
	s_nop 0
	global_load_lds_dwordx4 v[160:161], off
	v_lshl_add_u64 v[160:161], v[250:251], 0, s[22:23]
	s_mov_b32 m0, s82
	s_nop 0
	global_load_lds_dwordx4 v[160:161], off
	v_lshl_add_u64 v[160:161], v[252:253], 0, s[22:23]
	s_mov_b32 m0, s83
	s_nop 0
	global_load_lds_dwordx4 v[160:161], off
	s_waitcnt vmcnt(8)
	s_waitcnt lgkmcnt(0)
	s_barrier
	s_setprio 1
	s_waitcnt lgkmcnt(0)
	v_mfma_f32_16x16x32_bf16 v[62:65], v[130:133], v[216:219], v[62:65]
	v_mfma_f32_16x16x32_bf16 v[58:61], v[152:155], v[216:219], v[58:61]
	v_mfma_f32_16x16x32_bf16 v[46:49], v[130:133], v[224:227], v[46:49]
	v_mfma_f32_16x16x32_bf16 v[42:45], v[152:155], v[224:227], v[42:45]
	v_mfma_f32_16x16x32_bf16 v[30:33], v[130:133], v[232:235], v[30:33]
	v_mfma_f32_16x16x32_bf16 v[26:29], v[152:155], v[232:235], v[26:29]
	v_mfma_f32_16x16x32_bf16 v[14:17], v[130:133], v[240:243], v[14:17]
	v_mfma_f32_16x16x32_bf16 v[10:13], v[152:155], v[240:243], v[10:13]
	v_mfma_f32_16x16x32_bf16 v[62:65], v[148:151], v[220:223], v[62:65]
	v_mfma_f32_16x16x32_bf16 v[58:61], v[156:159], v[220:223], v[58:61]
	v_mfma_f32_16x16x32_bf16 v[46:49], v[148:151], v[228:231], v[46:49]
	v_mfma_f32_16x16x32_bf16 v[42:45], v[156:159], v[228:231], v[42:45]
	v_mfma_f32_16x16x32_bf16 v[30:33], v[148:151], v[236:239], v[30:33]
	v_mfma_f32_16x16x32_bf16 v[26:29], v[156:159], v[236:239], v[26:29]
	v_mfma_f32_16x16x32_bf16 v[14:17], v[148:151], v[244:247], v[14:17]
	v_mfma_f32_16x16x32_bf16 v[10:13], v[156:159], v[244:247], v[10:13]
	s_setprio 0
	s_setprio 1
	v_mfma_f32_16x16x32_bf16 v[54:57], v[170:173], v[216:219], v[54:57]
	v_mfma_f32_16x16x32_bf16 v[50:53], v[178:181], v[216:219], v[50:53]
	s_add_i32 s8, s8, 2
	v_mfma_f32_16x16x32_bf16 v[38:41], v[170:173], v[224:227], v[38:41]
	s_add_u32 s28, s28, 0x100
	v_mfma_f32_16x16x32_bf16 v[34:37], v[178:181], v[224:227], v[34:37]
	s_addc_u32 s29, s29, 0
	v_mfma_f32_16x16x32_bf16 v[22:25], v[170:173], v[232:235], v[22:25]
	s_add_u32 s7, s7, 0x100
	v_mfma_f32_16x16x32_bf16 v[18:21], v[178:181], v[232:235], v[18:21]
	s_addc_u32 s15, s15, 0
	v_mfma_f32_16x16x32_bf16 v[6:9], v[170:173], v[240:243], v[6:9]
	s_add_u32 s9, s28, 0xfff80080
	v_mfma_f32_16x16x32_bf16 v[2:5], v[178:181], v[240:243], v[2:5]
	s_addc_u32 s10, s29, -1
	v_mfma_f32_16x16x32_bf16 v[54:57], v[174:177], v[220:223], v[54:57]
	s_add_i32 s11, 0, 0x10000
	v_mfma_f32_16x16x32_bf16 v[50:53], v[202:205], v[220:223], v[50:53]
	s_cmp_eq_u32 s8, 28
	v_mfma_f32_16x16x32_bf16 v[38:41], v[174:177], v[228:231], v[38:41]
	s_cselect_b32 vcc_hi, s4, s10
	v_mfma_f32_16x16x32_bf16 v[34:37], v[202:205], v[228:231], v[34:37]
	s_cselect_b32 vcc_lo, s5, s9
	v_mfma_f32_16x16x32_bf16 v[22:25], v[174:177], v[236:239], v[22:25]
	s_cselect_b32 s45, s13, s15
	v_mfma_f32_16x16x32_bf16 v[18:21], v[202:205], v[236:239], v[18:21]
	s_cselect_b32 s44, s6, s7
	v_mfma_f32_16x16x32_bf16 v[6:9], v[174:177], v[244:247], v[6:9]
	s_add_i32 s9, 0, 0x14000
	v_mfma_f32_16x16x32_bf16 v[2:5], v[202:205], v[244:247], v[2:5]
	s_cmp_gt_u32 s8, 29
	s_setprio 0
	s_barrier
	s_cbranch_scc0 .Lrot_277
	s_and_b64 vcc, exec, s[60:61]
	s_cbranch_vccz .LBB0_280
	s_barrier
